# in-proj and up-proj: next unit's As[1][1] staging issued before the epilogue stores and the first iteration's three DMA waits counted as vmcnt(24), so the K-loop no longer waits for the stores to drai
# speedup vs baseline: 1.0071x; 1.0071x over previous
; #define PG8_LAS __attribute__((address_space(3)))
; #define FRESH_IDS() int wave = wave_k; asm volatile("" : "+s"(wave)); const int lane = pg8::fresh_lane(); const int tid = wave * 64 + lane; const int gw = bx * NWAVES + wave; (void)gw; (void)tid
; #define SS WSPTR(float, WS_SS)
; #define ROPE WSPTR(float, WS_ROPE)
; template <class Sched>
; __device__ __forceinline__ RsTable rs_prepass(PG8_LAS unsigned char* lds_spare, const float* ssp, const Sched& S, int tid) {
;     RsTable T; T.pm[0] = T.pm[1] = T.pm[2] = T.pm[3] = -1; T.tab = (const PG8_LAS float*)(lds_spare + 4096);
; __global__ void __launch_bounds__(NWAVES * 64, 2) hybrid_fwd(Args a) {
;     ...
;         { pg8::Gemm g{ACT, Wi + (size_t)l * INW * DM, M, INW, DM, DM}; pg8::StaticOrder S; S.init(M, INW, G, bx, WGM_IN);
;           FRESH_IDS(); const pg8::RsTable rst = pg8::rs_prepass(lds + 131072, SS, S, tid);
;           pg8::EpiInProj E{Z, ROPE, rst};
;           pg8::gemm_phase<pg8::EpiInProj, pg8::StaticOrder, true, true>(lds, g, S, E, wave_k); }
.LBB0_82:
	s_mov_b32 s100, 0
	s_xor_b64 s[0:1], s[4:5], -1
	v_writelane_b32 v251, s0, 47
	v_readlane_b32 s14, v252, 37
	s_mov_b32 s22, -1
	v_writelane_b32 v251, s1, 48
	v_readlane_b32 s0, v252, 13
	v_readlane_b32 s1, v252, 14
	v_readlane_b32 s2, v252, 15
	v_readlane_b32 s3, v252, 16
	s_mov_b64 s[4:5], s[2:3]
	s_mov_b64 s[6:7], s[2:3]
	s_mov_b64 s[0:1], s[2:3]
	s_mov_b64 s[2:3], s[94:95]
	s_mov_b32 s20, -1
	s_mov_b32 s19, -1
	s_mov_b32 s18, -1
	s_mov_b32 s15, -1
	s_mov_b32 s17, -1
	s_mov_b32 s21, -1
	s_mov_b32 s16, -1
	v_mbcnt_lo_u32_b32 v1, -1, 0
	v_mbcnt_hi_u32_b32 v1, -1, v1
	s_branch .LBB0_86

; #define PG8_STAGE(bufoff, gbase, voff) do { _Pragma("unroll") for (int _i = 0; _i < 2; ++_i) \
;         __builtin_amdgcn_global_load_lds((const unsigned*)((const char*)(gbase) + (voff)[_i]), (PG8_LAS unsigned*)(lds + (bufoff) + ldsw + _i * 8192), 16, 0, 0); } while (0)
; #define PG8_LDA(dst, b, h) do { _Pragma("unroll") for (int m = 0; m < 4; ++m) _Pragma("unroll") for (int k = 0; k < 2; ++k) dst[m][k] = *(const PG8_LAS bf16x8*)(lds + PG8_SA(b, h) + aoff + m * 2048 + k * 1024); } while (0)
; #define PG8_LDB(dst, b, h) do { _Pragma("unroll") for (int n = 0; n < 2; ++n) _Pragma("unroll") for (int k = 0; k < 2; ++k) dst[n][k] = *(const PG8_LAS bf16x8*)(lds + PG8_SB(b, h) + boff + n * 2048 + k * 1024); } while (0)
; #define PG8_MMA(ai, bj, At, Bt) do { __builtin_amdgcn_s_setprio(1); _Pragma("unroll") for (int m = 0; m < 4; ++m) _Pragma("unroll") for (int n = 0; n < 2; ++n) _Pragma("unroll") for (int k = 0; k < 2; ++k) \
;         acc[ai][bj][m][n] = __builtin_amdgcn_mfma_f32_16x16x32_bf16(Bt[n][k], At[m][k], acc[ai][bj][m][n], 0, 0, 0); __builtin_amdgcn_s_setprio(0); } while (0)
; #define PG8_WAIT_V(n) asm volatile("s_waitcnt vmcnt(" #n ")" ::: "memory")
; #define PG8_WAIT_L(n) asm volatile("s_waitcnt lgkmcnt(" #n ")" ::: "memory")
; template <class Epi, class Sched, bool ALIGN_EPI = false, bool SP2 = false>
; __device__ __forceinline__ void gemm_phase(PG8_LAS unsigned char* lds, const Gemm g, const Sched& S, const Epi& E, const int wid_in) {
;     ...
;             const bool last = (t == nt - 2);
;             const char* a1 = cA + (size_t)(t + 1) * kstep;
;             const char* a2 = last ? nA : cA + (size_t)(t + 2) * kstep; const char* b2 = last ? nB : cB + (size_t)(t + 2) * kstep;
;             const char* a3 = a2 + kstep; const char* b3 = b2 + kstep;
;             if (last && has_next) S.a_ready(nxt);
;             if constexpr (SP2) {
;             PG8_LDB(B0, 0, 0); PG8_LDB(B1, 0, 1); PG8_SCHED; PG8_LDA(At, 0, 0); PG8_STAGE(PG8_SA(1, 1), a1 + hstepA, voffA);
;             PG8_WAIT_V(8); PG8_WAIT_L(0); PG8_BAR; PG8_MMA(0, 0, At, B0); PG8_MMA(0, 1, At, B1); PG8_BAR; PG8_SCHED;
;             PG8_LDA(At, 0, 1); PG8_STAGE(PG8_SB(0, 0), b2, voffB); PG8_STAGE(PG8_SB(0, 1), b2 + hstep, voffB); PG8_STAGE(PG8_SA(0, 0), a2, voffA);
;             PG8_WAIT_V(8); PG8_WAIT_L(0); PG8_BAR; PG8_MMA(1, 0, At, B0); PG8_MMA(1, 1, At, B1); PG8_BAR; PG8_SCHED;
.LBB0_119:
	s_add_u32 s2, s4, 0xfff80080
	s_addc_u32 s3, s5, -1
	s_add_i32 s47, 0, 0x10000
	s_cmp_eq_u32 s46, 28
	s_cselect_b32 s23, s17, s3
	s_cselect_b32 s22, s42, s2
	s_cselect_b32 s3, s15, s45
	s_cselect_b32 s2, s43, s44
	s_add_i32 s50, 0, 0x14000
	v_add_u32_e32 v142, s47, v202
	s_waitcnt lgkmcnt(0)
	v_add_u32_e32 v184, s50, v202
	ds_read_b128 v[130:133], v142
	ds_read_b128 v[134:137], v142 offset:1024
	ds_read_b128 v[138:141], v142 offset:2048
	ds_read_b128 v[142:145], v142 offset:3072
	ds_read_b128 v[146:149], v184
	ds_read_b128 v[150:153], v184 offset:1024
	ds_read_b128 v[180:183], v184 offset:2048
	ds_read_b128 v[184:187], v184 offset:3072
	v_lshl_add_u64 v[234:235], s[4:5], 0, v[176:177]
	s_add_i32 m0, s34, 0xc000
	ds_read_b128 v[188:191], v205
	ds_read_b128 v[206:209], v205 offset:1024
	ds_read_b128 v[210:213], v205 offset:2048
	ds_read_b128 v[214:217], v205 offset:3072
	ds_read_b128 v[218:221], v205 offset:4096
	ds_read_b128 v[222:225], v205 offset:5120
	ds_read_b128 v[226:229], v205 offset:6144
	ds_read_b128 v[230:233], v205 offset:7168
	s_cmp_eq_u32 s100, 1
	s_cbranch_scc1 .Lrx_p1_skA
	global_load_lds_dwordx4 v[234:235], off
.Lrx_p1_skA:
	v_lshl_add_u64 v[234:235], s[4:5], 0, v[178:179]
	s_add_i32 m0, s34, 0xe000
	s_nop 0
	s_cmp_eq_u32 s100, 1
	s_cbranch_scc1 .Lrx_p1_skB
	global_load_lds_dwordx4 v[234:235], off
.Lrx_p1_skB:
	s_cmp_eq_u32 s100, 1
	s_cbranch_scc1 .Lrx_p1_w24_0
	s_waitcnt vmcnt(8)
	s_branch .Lrx_p1_wd_0
.Lrx_p1_w24_0:
	s_waitcnt vmcnt(24)
.Lrx_p1_wd_0:
	s_waitcnt lgkmcnt(0)
	s_setprio 1
	s_waitcnt lgkmcnt(0)
	v_mfma_f32_16x16x32_bf16 v[126:129], v[130:133], v[188:191], v[126:129]
	v_mfma_f32_16x16x32_bf16 v[122:125], v[138:141], v[188:191], v[122:125]
	s_barrier
	v_mfma_f32_16x16x32_bf16 v[110:113], v[130:133], v[210:213], v[110:113]
	v_mfma_f32_16x16x32_bf16 v[106:109], v[138:141], v[210:213], v[106:109]
	v_mfma_f32_16x16x32_bf16 v[94:97], v[130:133], v[218:221], v[94:97]
	v_mfma_f32_16x16x32_bf16 v[90:93], v[138:141], v[218:221], v[90:93]
	v_mfma_f32_16x16x32_bf16 v[78:81], v[130:133], v[226:229], v[78:81]
	v_mfma_f32_16x16x32_bf16 v[74:77], v[138:141], v[226:229], v[74:77]
	v_mfma_f32_16x16x32_bf16 v[126:129], v[134:137], v[206:209], v[126:129]
	v_mfma_f32_16x16x32_bf16 v[122:125], v[142:145], v[206:209], v[122:125]
	v_mfma_f32_16x16x32_bf16 v[110:113], v[134:137], v[214:217], v[110:113]
	v_mfma_f32_16x16x32_bf16 v[106:109], v[142:145], v[214:217], v[106:109]
	v_mfma_f32_16x16x32_bf16 v[94:97], v[134:137], v[222:225], v[94:97]
	v_mfma_f32_16x16x32_bf16 v[90:93], v[142:145], v[222:225], v[90:93]
	v_mfma_f32_16x16x32_bf16 v[78:81], v[134:137], v[230:233], v[78:81]
	v_mfma_f32_16x16x32_bf16 v[74:77], v[142:145], v[230:233], v[74:77]
	s_setprio 0
	s_setprio 1
	v_mfma_f32_16x16x32_bf16 v[118:121], v[146:149], v[188:191], v[118:121]
	v_mfma_f32_16x16x32_bf16 v[114:117], v[180:183], v[188:191], v[114:117]
	v_mfma_f32_16x16x32_bf16 v[102:105], v[146:149], v[210:213], v[102:105]
	v_mfma_f32_16x16x32_bf16 v[98:101], v[180:183], v[210:213], v[98:101]
	v_mfma_f32_16x16x32_bf16 v[86:89], v[146:149], v[218:221], v[86:89]
	v_mfma_f32_16x16x32_bf16 v[82:85], v[180:183], v[218:221], v[82:85]
	v_mfma_f32_16x16x32_bf16 v[70:73], v[146:149], v[226:229], v[70:73]
	v_mfma_f32_16x16x32_bf16 v[66:69], v[180:183], v[226:229], v[66:69]
	v_mfma_f32_16x16x32_bf16 v[118:121], v[150:153], v[206:209], v[118:121]
	v_mfma_f32_16x16x32_bf16 v[114:117], v[184:187], v[206:209], v[114:117]
	v_mfma_f32_16x16x32_bf16 v[102:105], v[150:153], v[214:217], v[102:105]
	v_mfma_f32_16x16x32_bf16 v[98:101], v[184:187], v[214:217], v[98:101]
	v_mfma_f32_16x16x32_bf16 v[86:89], v[150:153], v[222:225], v[86:89]
	v_mfma_f32_16x16x32_bf16 v[82:85], v[184:187], v[222:225], v[82:85]
	v_mfma_f32_16x16x32_bf16 v[70:73], v[150:153], v[230:233], v[70:73]
	v_mfma_f32_16x16x32_bf16 v[66:69], v[184:187], v[230:233], v[66:69]
	s_setprio 0
	s_barrier
	s_add_i32 s47, s47, s27
	v_lshl_add_u64 v[234:235], s[2:3], 0, v[170:171]
	s_mov_b32 m0, s47
	ds_read_b128 v[188:191], v205 offset:16384
	ds_read_b128 v[206:209], v205 offset:17408
	ds_read_b128 v[210:213], v205 offset:18432
	ds_read_b128 v[214:217], v205 offset:19456
	ds_read_b128 v[218:221], v205 offset:20480
	ds_read_b128 v[222:225], v205 offset:21504
	ds_read_b128 v[226:229], v205 offset:22528
	ds_read_b128 v[230:233], v205 offset:23552
	global_load_lds_dwordx4 v[234:235], off
	s_add_i32 m0, s47, 0x2000
	s_add_u32 s48, s2, 0x80000
	v_lshl_add_u64 v[236:237], s[2:3], 0, v[166:167]
	s_addc_u32 s49, s3, 0
	s_add_i32 s47, s50, s27
	global_load_lds_dwordx4 v[236:237], off
	v_lshl_add_u64 v[238:239], s[48:49], 0, v[170:171]
	s_mov_b32 m0, s47
	v_lshl_add_u64 v[240:241], s[22:23], 0, v[168:169]
	global_load_lds_dwordx4 v[238:239], off
	v_lshl_add_u64 v[238:239], s[48:49], 0, v[166:167]
	s_add_i32 m0, s47, 0x2000
	s_nop 0
	global_load_lds_dwordx4 v[238:239], off
	v_lshl_add_u64 v[238:239], s[22:23], 0, v[172:173]
	s_mov_b32 m0, s34
	s_nop 0
	global_load_lds_dwordx4 v[238:239], off
	s_mov_b32 m0, s35
	s_nop 0
	global_load_lds_dwordx4 v[240:241], off
	s_cmp_eq_u32 s100, 1
	s_cbranch_scc1 .Lrx_p1_w24_1
	s_waitcnt vmcnt(8)
	s_branch .Lrx_p1_wd_1

; #define PG8_STAGE(bufoff, gbase, voff) do { _Pragma("unroll") for (int _i = 0; _i < 2; ++_i) \
;         __builtin_amdgcn_global_load_lds((const unsigned*)((const char*)(gbase) + (voff)[_i]), (PG8_LAS unsigned*)(lds + (bufoff) + ldsw + _i * 8192), 16, 0, 0); } while (0)
; #define PG8_LDA(dst, b, h) do { _Pragma("unroll") for (int m = 0; m < 4; ++m) _Pragma("unroll") for (int k = 0; k < 2; ++k) dst[m][k] = *(const PG8_LAS bf16x8*)(lds + PG8_SA(b, h) + aoff + m * 2048 + k * 1024); } while (0)
; #define PG8_LDB(dst, b, h) do { _Pragma("unroll") for (int n = 0; n < 2; ++n) _Pragma("unroll") for (int k = 0; k < 2; ++k) dst[n][k] = *(const PG8_LAS bf16x8*)(lds + PG8_SB(b, h) + boff + n * 2048 + k * 1024); } while (0)
; #define PG8_MMA(ai, bj, At, Bt) do { __builtin_amdgcn_s_setprio(1); _Pragma("unroll") for (int m = 0; m < 4; ++m) _Pragma("unroll") for (int n = 0; n < 2; ++n) _Pragma("unroll") for (int k = 0; k < 2; ++k) \
;         acc[ai][bj][m][n] = __builtin_amdgcn_mfma_f32_16x16x32_bf16(Bt[n][k], At[m][k], acc[ai][bj][m][n], 0, 0, 0); __builtin_amdgcn_s_setprio(0); } while (0)
; #define PG8_WAIT_V(n) asm volatile("s_waitcnt vmcnt(" #n ")" ::: "memory")
; #define PG8_WAIT_L(n) asm volatile("s_waitcnt lgkmcnt(" #n ")" ::: "memory")
; #define PG8_BAR __builtin_amdgcn_s_barrier()
; #define PG8_SCHED __builtin_amdgcn_sched_barrier(0)
; template <class Epi, class Sched, bool ALIGN_EPI = false, bool SP2 = false>
; __device__ __forceinline__ void gemm_phase(PG8_LAS unsigned char* lds, const Gemm g, const Sched& S, const Epi& E, const int wid_in) {
;     ...
;             PG8_WAIT_V(8); PG8_WAIT_L(0); PG8_BAR; PG8_MMA(1, 0, At, B0); PG8_MMA(1, 1, At, B1); PG8_BAR; PG8_SCHED;
;             PG8_LDB(B0, 1, 0); PG8_LDB(B1, 1, 1); PG8_SCHED; PG8_LDA(At, 1, 0); PG8_STAGE(PG8_SA(0, 1), a2 + hstepA, voffA);
;             PG8_WAIT_V(8); PG8_WAIT_L(0); PG8_BAR; PG8_MMA(0, 0, At, B0); PG8_MMA(0, 1, At, B1); PG8_BAR; PG8_SCHED;
.Lrx_p1_wd_1:
	s_waitcnt lgkmcnt(0)
	s_setprio 1
	s_waitcnt lgkmcnt(0)
	v_mfma_f32_16x16x32_bf16 v[62:65], v[130:133], v[188:191], v[62:65]
	v_mfma_f32_16x16x32_bf16 v[58:61], v[138:141], v[188:191], v[58:61]
	s_barrier
	v_mfma_f32_16x16x32_bf16 v[46:49], v[130:133], v[210:213], v[46:49]
	v_mfma_f32_16x16x32_bf16 v[42:45], v[138:141], v[210:213], v[42:45]
	v_mfma_f32_16x16x32_bf16 v[30:33], v[130:133], v[218:221], v[30:33]
	v_mfma_f32_16x16x32_bf16 v[26:29], v[138:141], v[218:221], v[26:29]
	v_mfma_f32_16x16x32_bf16 v[14:17], v[130:133], v[226:229], v[14:17]
	v_mfma_f32_16x16x32_bf16 v[10:13], v[138:141], v[226:229], v[10:13]
	v_mfma_f32_16x16x32_bf16 v[62:65], v[134:137], v[206:209], v[62:65]
	v_mfma_f32_16x16x32_bf16 v[58:61], v[142:145], v[206:209], v[58:61]
	v_mfma_f32_16x16x32_bf16 v[46:49], v[134:137], v[214:217], v[46:49]
	v_mfma_f32_16x16x32_bf16 v[42:45], v[142:145], v[214:217], v[42:45]
	v_mfma_f32_16x16x32_bf16 v[30:33], v[134:137], v[222:225], v[30:33]
	v_mfma_f32_16x16x32_bf16 v[26:29], v[142:145], v[222:225], v[26:29]
	v_mfma_f32_16x16x32_bf16 v[14:17], v[134:137], v[230:233], v[14:17]
	v_mfma_f32_16x16x32_bf16 v[10:13], v[142:145], v[230:233], v[10:13]
	s_setprio 0
	s_setprio 1
	v_mfma_f32_16x16x32_bf16 v[54:57], v[146:149], v[188:191], v[54:57]
	v_mfma_f32_16x16x32_bf16 v[50:53], v[180:183], v[188:191], v[50:53]
	v_mfma_f32_16x16x32_bf16 v[38:41], v[146:149], v[210:213], v[38:41]
	v_mfma_f32_16x16x32_bf16 v[34:37], v[180:183], v[210:213], v[34:37]
	v_mfma_f32_16x16x32_bf16 v[22:25], v[146:149], v[218:221], v[22:25]
	v_mfma_f32_16x16x32_bf16 v[18:21], v[180:183], v[218:221], v[18:21]
	v_mfma_f32_16x16x32_bf16 v[6:9], v[146:149], v[226:229], v[6:9]
	v_mfma_f32_16x16x32_bf16 v[2:5], v[180:183], v[226:229], v[2:5]
	v_mfma_f32_16x16x32_bf16 v[54:57], v[150:153], v[206:209], v[54:57]
	v_mfma_f32_16x16x32_bf16 v[50:53], v[184:187], v[206:209], v[50:53]
	v_mfma_f32_16x16x32_bf16 v[38:41], v[150:153], v[214:217], v[38:41]
	v_mfma_f32_16x16x32_bf16 v[34:37], v[184:187], v[214:217], v[34:37]
	v_mfma_f32_16x16x32_bf16 v[22:25], v[150:153], v[222:225], v[22:25]
	v_mfma_f32_16x16x32_bf16 v[18:21], v[184:187], v[222:225], v[18:21]
	v_mfma_f32_16x16x32_bf16 v[6:9], v[150:153], v[230:233], v[6:9]
	v_mfma_f32_16x16x32_bf16 v[2:5], v[184:187], v[230:233], v[2:5]
	s_setprio 0
	s_barrier
	s_add_i32 s47, 0, 0x18000
	s_add_i32 s48, 0, 0x1c000
	v_add_u32_e32 v142, s47, v202
	v_add_u32_e32 v184, s48, v202
	ds_read_b128 v[130:133], v142
	ds_read_b128 v[134:137], v142 offset:1024
	ds_read_b128 v[138:141], v142 offset:2048
	ds_read_b128 v[142:145], v142 offset:3072
	ds_read_b128 v[146:149], v184
	ds_read_b128 v[150:153], v184 offset:1024
	ds_read_b128 v[180:183], v184 offset:2048
	ds_read_b128 v[184:187], v184 offset:3072
	s_add_u32 s22, s22, 0x80000
	s_addc_u32 s23, s23, 0
	s_mov_b32 m0, s36
	v_lshl_add_u64 v[242:243], s[22:23], 0, v[172:173]
	ds_read_b128 v[188:191], v205 offset:32768
	ds_read_b128 v[206:209], v205 offset:33792
	ds_read_b128 v[210:213], v205 offset:34816
	ds_read_b128 v[214:217], v205 offset:35840
	ds_read_b128 v[218:221], v205 offset:36864
	ds_read_b128 v[222:225], v205 offset:37888
	ds_read_b128 v[226:229], v205 offset:38912
	ds_read_b128 v[230:233], v205 offset:39936
	global_load_lds_dwordx4 v[242:243], off
	v_lshl_add_u64 v[242:243], s[22:23], 0, v[168:169]
	s_mov_b32 m0, s37
	s_nop 0
	global_load_lds_dwordx4 v[242:243], off
	s_cmp_eq_u32 s100, 1
	s_cbranch_scc1 .Lrx_p1_w24_2
	s_waitcnt vmcnt(8)
	s_branch .Lrx_p1_wd_2

; #define PG8_STAGE(bufoff, gbase, voff) do { _Pragma("unroll") for (int _i = 0; _i < 2; ++_i) \
;         __builtin_amdgcn_global_load_lds((const unsigned*)((const char*)(gbase) + (voff)[_i]), (PG8_LAS unsigned*)(lds + (bufoff) + ldsw + _i * 8192), 16, 0, 0); } while (0)
; #define PG8_LDA(dst, b, h) do { _Pragma("unroll") for (int m = 0; m < 4; ++m) _Pragma("unroll") for (int k = 0; k < 2; ++k) dst[m][k] = *(const PG8_LAS bf16x8*)(lds + PG8_SA(b, h) + aoff + m * 2048 + k * 1024); } while (0)
; #define PG8_MMA(ai, bj, At, Bt) do { __builtin_amdgcn_s_setprio(1); _Pragma("unroll") for (int m = 0; m < 4; ++m) _Pragma("unroll") for (int n = 0; n < 2; ++n) _Pragma("unroll") for (int k = 0; k < 2; ++k) \
;         acc[ai][bj][m][n] = __builtin_amdgcn_mfma_f32_16x16x32_bf16(Bt[n][k], At[m][k], acc[ai][bj][m][n], 0, 0, 0); __builtin_amdgcn_s_setprio(0); } while (0)
; #define PG8_WAIT_V(n) asm volatile("s_waitcnt vmcnt(" #n ")" ::: "memory")
; #define PG8_WAIT_L(n) asm volatile("s_waitcnt lgkmcnt(" #n ")" ::: "memory")
; #define PG8_BAR __builtin_amdgcn_s_barrier()
; #define PG8_SCHED __builtin_amdgcn_sched_barrier(0)
; template <class Epi, class Sched, bool ALIGN_EPI = false, bool SP2 = false>
; __device__ __forceinline__ void gemm_phase(PG8_LAS unsigned char* lds, const Gemm g, const Sched& S, const Epi& E, const int wid_in) {
;     ...
;             PG8_WAIT_V(8); PG8_WAIT_L(0); PG8_BAR; PG8_MMA(0, 0, At, B0); PG8_MMA(0, 1, At, B1); PG8_BAR; PG8_SCHED;
;             PG8_LDA(At, 1, 1); PG8_STAGE(PG8_SB(1, 0), b3, voffB); PG8_STAGE(PG8_SB(1, 1), b3 + hstep, voffB); PG8_STAGE(PG8_SA(1, 0), a3, voffA);
;             PG8_WAIT_V(8); PG8_WAIT_L(0); PG8_BAR; PG8_MMA(1, 0, At, B0); PG8_MMA(1, 1, At, B1); PG8_BAR; PG8_SCHED;
.Lrx_p1_wd_2:
	s_waitcnt lgkmcnt(0)
	s_setprio 1
	s_waitcnt lgkmcnt(0)
	v_mfma_f32_16x16x32_bf16 v[126:129], v[130:133], v[188:191], v[126:129]
	v_mfma_f32_16x16x32_bf16 v[122:125], v[138:141], v[188:191], v[122:125]
	s_barrier
	v_mfma_f32_16x16x32_bf16 v[110:113], v[130:133], v[210:213], v[110:113]
	v_mfma_f32_16x16x32_bf16 v[106:109], v[138:141], v[210:213], v[106:109]
	v_mfma_f32_16x16x32_bf16 v[94:97], v[130:133], v[218:221], v[94:97]
	v_mfma_f32_16x16x32_bf16 v[90:93], v[138:141], v[218:221], v[90:93]
	v_mfma_f32_16x16x32_bf16 v[78:81], v[130:133], v[226:229], v[78:81]
	v_mfma_f32_16x16x32_bf16 v[74:77], v[138:141], v[226:229], v[74:77]
	v_mfma_f32_16x16x32_bf16 v[126:129], v[134:137], v[206:209], v[126:129]
	v_mfma_f32_16x16x32_bf16 v[122:125], v[142:145], v[206:209], v[122:125]
	v_mfma_f32_16x16x32_bf16 v[110:113], v[134:137], v[214:217], v[110:113]
	v_mfma_f32_16x16x32_bf16 v[106:109], v[142:145], v[214:217], v[106:109]
	v_mfma_f32_16x16x32_bf16 v[94:97], v[134:137], v[222:225], v[94:97]
	v_mfma_f32_16x16x32_bf16 v[90:93], v[142:145], v[222:225], v[90:93]
	v_mfma_f32_16x16x32_bf16 v[78:81], v[134:137], v[230:233], v[78:81]
	v_mfma_f32_16x16x32_bf16 v[74:77], v[142:145], v[230:233], v[74:77]
	s_setprio 0
	s_setprio 1
	v_mfma_f32_16x16x32_bf16 v[118:121], v[146:149], v[188:191], v[118:121]
	v_mfma_f32_16x16x32_bf16 v[114:117], v[180:183], v[188:191], v[114:117]
	v_mfma_f32_16x16x32_bf16 v[102:105], v[146:149], v[210:213], v[102:105]
	v_mfma_f32_16x16x32_bf16 v[98:101], v[180:183], v[210:213], v[98:101]
	v_mfma_f32_16x16x32_bf16 v[86:89], v[146:149], v[218:221], v[86:89]
	v_mfma_f32_16x16x32_bf16 v[82:85], v[180:183], v[218:221], v[82:85]
	v_mfma_f32_16x16x32_bf16 v[70:73], v[146:149], v[226:229], v[70:73]
	v_mfma_f32_16x16x32_bf16 v[66:69], v[180:183], v[226:229], v[66:69]
	v_mfma_f32_16x16x32_bf16 v[118:121], v[150:153], v[206:209], v[118:121]
	v_mfma_f32_16x16x32_bf16 v[114:117], v[184:187], v[206:209], v[114:117]
	v_mfma_f32_16x16x32_bf16 v[102:105], v[150:153], v[214:217], v[102:105]
	v_mfma_f32_16x16x32_bf16 v[98:101], v[184:187], v[214:217], v[98:101]
	v_mfma_f32_16x16x32_bf16 v[86:89], v[150:153], v[222:225], v[86:89]
	v_mfma_f32_16x16x32_bf16 v[82:85], v[184:187], v[222:225], v[82:85]
	v_mfma_f32_16x16x32_bf16 v[70:73], v[150:153], v[230:233], v[70:73]
	v_mfma_f32_16x16x32_bf16 v[66:69], v[184:187], v[230:233], v[66:69]
	s_setprio 0
	s_barrier
	s_add_i32 s22, s47, s27
	v_lshl_add_u64 v[234:235], v[234:235], 0, s[98:99]
	s_mov_b32 m0, s22
	ds_read_b128 v[188:191], v205 offset:49152
	ds_read_b128 v[206:209], v205 offset:50176
	ds_read_b128 v[210:213], v205 offset:51200
	ds_read_b128 v[214:217], v205 offset:52224
	ds_read_b128 v[218:221], v205 offset:53248
	ds_read_b128 v[222:225], v205 offset:54272
	ds_read_b128 v[226:229], v205 offset:55296
	ds_read_b128 v[230:233], v205 offset:56320
	global_load_lds_dwordx4 v[234:235], off
	s_add_i32 m0, s22, 0x2000
	s_add_u32 s2, s2, 0x80080
	v_lshl_add_u64 v[234:235], v[236:237], 0, s[98:99]
	s_addc_u32 s3, s3, 0
	s_add_i32 s22, s48, s27
	global_load_lds_dwordx4 v[234:235], off
	v_lshl_add_u64 v[234:235], s[2:3], 0, v[170:171]
	s_mov_b32 m0, s22
	s_nop 0
	global_load_lds_dwordx4 v[234:235], off
	v_lshl_add_u64 v[234:235], s[2:3], 0, v[166:167]
	s_add_i32 m0, s22, 0x2000
	s_nop 0
	global_load_lds_dwordx4 v[234:235], off
	v_lshl_add_u64 v[234:235], v[238:239], 0, s[98:99]
	s_mov_b32 m0, s38
	s_nop 0
	global_load_lds_dwordx4 v[234:235], off
	v_lshl_add_u64 v[234:235], v[240:241], 0, s[98:99]
	s_mov_b32 m0, s39
	s_nop 0
	global_load_lds_dwordx4 v[234:235], off
	s_waitcnt vmcnt(8)
	s_waitcnt lgkmcnt(0)
	s_setprio 1
	s_waitcnt lgkmcnt(0)
	v_mfma_f32_16x16x32_bf16 v[62:65], v[130:133], v[188:191], v[62:65]
	v_mfma_f32_16x16x32_bf16 v[58:61], v[138:141], v[188:191], v[58:61]
	s_barrier
	v_mfma_f32_16x16x32_bf16 v[46:49], v[130:133], v[210:213], v[46:49]
	v_mfma_f32_16x16x32_bf16 v[42:45], v[138:141], v[210:213], v[42:45]
	v_mfma_f32_16x16x32_bf16 v[30:33], v[130:133], v[218:221], v[30:33]
	v_mfma_f32_16x16x32_bf16 v[26:29], v[138:141], v[218:221], v[26:29]
	v_mfma_f32_16x16x32_bf16 v[14:17], v[130:133], v[226:229], v[14:17]
	v_mfma_f32_16x16x32_bf16 v[10:13], v[138:141], v[226:229], v[10:13]
	v_mfma_f32_16x16x32_bf16 v[62:65], v[134:137], v[206:209], v[62:65]
	v_mfma_f32_16x16x32_bf16 v[58:61], v[142:145], v[206:209], v[58:61]
	v_mfma_f32_16x16x32_bf16 v[46:49], v[134:137], v[214:217], v[46:49]
	v_mfma_f32_16x16x32_bf16 v[42:45], v[142:145], v[214:217], v[42:45]
	v_mfma_f32_16x16x32_bf16 v[30:33], v[134:137], v[222:225], v[30:33]
	v_mfma_f32_16x16x32_bf16 v[26:29], v[142:145], v[222:225], v[26:29]
	v_mfma_f32_16x16x32_bf16 v[14:17], v[134:137], v[230:233], v[14:17]
	v_mfma_f32_16x16x32_bf16 v[10:13], v[142:145], v[230:233], v[10:13]
	s_setprio 0
	s_setprio 1
	v_mfma_f32_16x16x32_bf16 v[54:57], v[146:149], v[188:191], v[54:57]
	v_mfma_f32_16x16x32_bf16 v[50:53], v[180:183], v[188:191], v[50:53]
	v_mfma_f32_16x16x32_bf16 v[38:41], v[146:149], v[210:213], v[38:41]
	v_mfma_f32_16x16x32_bf16 v[34:37], v[180:183], v[210:213], v[34:37]
	v_mfma_f32_16x16x32_bf16 v[22:25], v[146:149], v[218:221], v[22:25]
	v_mfma_f32_16x16x32_bf16 v[18:21], v[180:183], v[218:221], v[18:21]
	v_mfma_f32_16x16x32_bf16 v[6:9], v[146:149], v[226:229], v[6:9]
	v_mfma_f32_16x16x32_bf16 v[2:5], v[180:183], v[226:229], v[2:5]
	v_mfma_f32_16x16x32_bf16 v[54:57], v[150:153], v[206:209], v[54:57]
	v_mfma_f32_16x16x32_bf16 v[50:53], v[184:187], v[206:209], v[50:53]
	v_mfma_f32_16x16x32_bf16 v[38:41], v[150:153], v[214:217], v[38:41]
	v_mfma_f32_16x16x32_bf16 v[34:37], v[184:187], v[214:217], v[34:37]
	v_mfma_f32_16x16x32_bf16 v[22:25], v[150:153], v[222:225], v[22:25]
	v_mfma_f32_16x16x32_bf16 v[18:21], v[184:187], v[222:225], v[18:21]
	v_mfma_f32_16x16x32_bf16 v[6:9], v[150:153], v[230:233], v[6:9]
	v_mfma_f32_16x16x32_bf16 v[2:5], v[184:187], v[230:233], v[2:5]
	s_setprio 0
	s_barrier
	s_mov_b32 s100, 0
	s_add_i32 s46, s46, 2
	s_add_u32 s4, s4, 0x100
	s_addc_u32 s5, s5, 0
	s_add_u32 s44, s44, 0x100
	s_addc_u32 s45, s45, 0
	s_cmp_gt_u32 s46, 29
	s_cbranch_scc0 .LBB0_119
	s_and_b64 vcc, exec, s[12:13]
	s_cbranch_vccz .LBB0_122
	s_barrier
; __device__ __forceinline__ float gelu_tanh(float x) {
;     const float y = x * (0.7978845608028654f + 0.7978845608028654f * 0.044715f * x * x);
;     const float e = __builtin_amdgcn_exp2f(-2.0f * 1.4426950408889634f * y);
;     return x * __builtin_amdgcn_rcpf(1.0f + e);
; }
;     __device__ __forceinline__ void operator()(const f32x4 (&acc)[2][2][4][2], const Unit& u, int wr, int wc, int fr, int fq) const {
;     ...
;             for (int i = 0; i < 8; ++i) {
;                 const int ai = i >> 2, m = i & 3; bf16_t* rowp = Z + (size_t)(row0 + ai * HALF + m * 16) * 5120 + col0;
; #pragma unroll
;                 for (int bj = 0; bj < 2; ++bj) {
;                     f32x4 v0 = acc[ai][bj][m][0] * rs[i], v1 = acc[ai][bj][m][1] * rs[i];
;                     if (kind == 2) {
; #pragma unroll
;                         for (int e = 0; e < 4; ++e) { v0[e] = gelu_tanh(v0[e]); v1[e] = gelu_tanh(v1[e]); }
.LBB0_122:
	s_add_u32 s100, s42, 0x80080
	s_addc_u32 s101, s17, 0
	s_add_i32 m0, s34, 0xc000
	v_lshl_add_u64 v[234:235], s[100:101], 0, v[176:177]
	global_load_lds_dwordx4 v[234:235], off
	s_add_i32 m0, s34, 0xe000
	v_lshl_add_u64 v[234:235], s[100:101], 0, v[178:179]
	global_load_lds_dwordx4 v[234:235], off
	s_mov_b32 s100, 1
	s_cmp_gt_i32 s41, 11
	s_cselect_b64 s[2:3], -1, 0
	s_and_b32 s4, s41, -4
	s_cmp_eq_u32 s4, 4
	s_cselect_b64 s[4:5], -1, 0
	s_cmp_eq_u32 s33, s26
	s_cselect_b32 s15, 0x200, s56
	s_cmp_lg_u32 s33, s25
	s_cselect_b32 s15, s15, 0x100
	s_cmp_lg_u32 s33, s24
	s_cselect_b32 s15, s15, 0
	v_lshl_add_u32 v130, s15, 2, v204
	ds_read2_b32 v[186:187], v130 offset1:16
	ds_read2_b32 v[184:185], v130 offset0:32 offset1:48
	ds_read2_b32 v[182:183], v130 offset0:128 offset1:144
	ds_read2_b32 v[180:181], v130 offset0:160 offset1:176
	v_lshl_add_u32 v188, s41, 8, v203
	s_or_b64 s[22:23], s[2:3], s[4:5]
	v_lshl_add_u32 v206, s33, 8, v1
	v_ashrrev_i32_e32 v189, 31, v188
	s_mov_b64 s[4:5], -1
	s_and_b64 vcc, exec, s[22:23]
	s_cbranch_vccz .LBB0_156
	v_cndmask_b32_e64 v130, 0, 1, s[2:3]
	s_waitcnt lgkmcnt(0)
	v_pk_mul_f32 v[132:133], v[128:129], v[186:187] op_sel_hi:[1,0]
	v_pk_mul_f32 v[136:137], v[126:127], v[186:187] op_sel_hi:[1,0]
	v_pk_mul_f32 v[134:135], v[124:125], v[186:187] op_sel_hi:[1,0]
	v_cmp_ne_u32_e64 s[4:5], 1, v130
	s_andn2_b64 vcc, exec, s[2:3]
	v_pk_mul_f32 v[138:139], v[122:123], v[186:187] op_sel_hi:[1,0]
	s_cbranch_vccnz .LBB0_125
	v_mul_f32_e32 v131, 0x3d122279, v138
	v_fmaak_f32 v131, v138, v131, 0x3f4c422a
	v_mul_f32_e32 v131, v138, v131
	v_mul_f32_e32 v131, 0xc038aa3b, v131
	v_exp_f32_e32 v131, v131
	v_mul_f32_e32 v130, 0x3d122279, v136
	v_fmaak_f32 v130, v136, v130, 0x3f4c422a
	v_mul_f32_e32 v130, v136, v130
	v_add_f32_e32 v131, 1.0, v131
	v_rcp_f32_e32 v140, v131
	v_mul_f32_e32 v131, 0x3d122279, v137
	v_fmaak_f32 v131, v137, v131, 0x3f4c422a
	v_mul_f32_e32 v131, v137, v131
	v_mul_f32_e32 v130, 0xc038aa3b, v130
	v_mul_f32_e32 v131, 0xc038aa3b, v131
	v_exp_f32_e32 v130, v130
	v_exp_f32_e32 v131, v131
	v_mul_f32_e32 v143, 0x3d122279, v134
	v_fmaak_f32 v143, v134, v143, 0x3f4c422a
	v_mul_f32_e32 v143, v134, v143
	v_mul_f32_e32 v143, 0xc038aa3b, v143
	v_add_f32_e32 v130, 1.0, v130
	v_add_f32_e32 v131, 1.0, v131
	v_exp_f32_e32 v143, v143
	v_rcp_f32_e32 v130, v130
	v_rcp_f32_e32 v131, v131
	v_mul_f32_e32 v141, 0x3d122279, v139
	v_add_f32_e32 v143, 1.0, v143
	v_mul_f32_e32 v142, 0x3d122279, v132
	v_rcp_f32_e32 v144, v143
	v_mul_f32_e32 v143, 0x3d122279, v133
	v_pk_mul_f32 v[136:137], v[136:137], v[130:131]
	v_mul_f32_e32 v130, 0x3d122279, v135
	v_fmaak_f32 v141, v139, v141, 0x3f4c422a
	v_fmaak_f32 v142, v132, v142, 0x3f4c422a
	v_fmaak_f32 v143, v133, v143, 0x3f4c422a
	v_fmaak_f32 v130, v135, v130, 0x3f4c422a
	v_mul_f32_e32 v141, v139, v141
	v_mul_f32_e32 v142, v132, v142
	v_mul_f32_e32 v143, v133, v143
	v_mul_f32_e32 v130, v135, v130
	v_mul_f32_e32 v141, 0xc038aa3b, v141
	v_mul_f32_e32 v142, 0xc038aa3b, v142
	v_mul_f32_e32 v143, 0xc038aa3b, v143
	v_mul_f32_e32 v130, 0xc038aa3b, v130
	v_exp_f32_e32 v141, v141
	v_exp_f32_e32 v142, v142
	v_exp_f32_e32 v143, v143
	v_exp_f32_e32 v130, v130
	v_add_f32_e32 v141, 1.0, v141
	v_add_f32_e32 v142, 1.0, v142
	v_add_f32_e32 v143, 1.0, v143
	v_add_f32_e32 v130, 1.0, v130
	v_rcp_f32_e32 v141, v141
	v_rcp_f32_e32 v142, v142
	v_rcp_f32_e32 v143, v143
	v_rcp_f32_e32 v145, v130
	v_pk_mul_f32 v[138:139], v[138:139], v[140:141]
	v_pk_mul_f32 v[132:133], v[132:133], v[142:143]
	v_pk_mul_f32 v[134:135], v[134:135], v[144:145]

; #define PG8_LAS __attribute__((address_space(3)))
; #define FRESH_IDS() int wave = wave_k; asm volatile("" : "+s"(wave)); const int lane = pg8::fresh_lane(); const int tid = wave * 64 + lane; const int gw = bx * NWAVES + wave; (void)gw; (void)tid
; #define SS WSPTR(float, WS_SS)
; template <class Sched>
; __device__ __forceinline__ RsTable rs_prepass(PG8_LAS unsigned char* lds_spare, const float* ssp, const Sched& S, int tid) {
;     RsTable T; T.pm[0] = T.pm[1] = T.pm[2] = T.pm[3] = -1; T.tab = (const PG8_LAS float*)(lds_spare + 4096);
; __global__ void __launch_bounds__(NWAVES * 64, 2) hybrid_fwd(Args a) {
;     ...
;         { pg8::Gemm g{ACT, Wu + (size_t)l * DFF * DM, M, DFF, DM, DM}; pg8::StaticOrder S; S.init(M, DFF, G, bx, WGM_UP);
;           FRESH_IDS(); const pg8::RsTable rst = pg8::rs_prepass(lds + 131072, SS, S, tid);
.LBB0_439:
	s_or_b64 exec, exec, s[0:1]
	v_readlane_b32 s0, v252, 13
	v_readlane_b32 s1, v252, 14
	v_readlane_b32 s2, v252, 15
	v_readlane_b32 s3, v252, 16
	s_mov_b64 s[10:11], s[2:3]
	s_mov_b64 s[12:13], s[2:3]
	v_readlane_b32 s16, v252, 37
	s_mov_b64 s[0:1], s[2:3]
	s_mov_b32 s23, -1
	s_mov_b64 s[2:3], s[94:95]
	s_mov_b32 s22, -1
	s_mov_b32 s21, -1
	s_mov_b32 s20, -1
	s_mov_b32 s17, -1
	s_mov_b32 s19, -1
	s_mov_b32 s24, -1
	s_mov_b32 s18, -1
	s_waitcnt lgkmcnt(0)
	s_barrier
	s_mov_b32 s100, 0
	v_mbcnt_lo_u32_b32 v1, -1, 0
	v_mbcnt_hi_u32_b32 v1, -1, v1
	s_branch .LBB0_443

; #define PG8_STAGE(bufoff, gbase, voff) do { _Pragma("unroll") for (int _i = 0; _i < 2; ++_i) \
;         __builtin_amdgcn_global_load_lds((const unsigned*)((const char*)(gbase) + (voff)[_i]), (PG8_LAS unsigned*)(lds + (bufoff) + ldsw + _i * 8192), 16, 0, 0); } while (0)
; #define PG8_LDA(dst, b, h) do { _Pragma("unroll") for (int m = 0; m < 4; ++m) _Pragma("unroll") for (int k = 0; k < 2; ++k) dst[m][k] = *(const PG8_LAS bf16x8*)(lds + PG8_SA(b, h) + aoff + m * 2048 + k * 1024); } while (0)
; #define PG8_LDB(dst, b, h) do { _Pragma("unroll") for (int n = 0; n < 2; ++n) _Pragma("unroll") for (int k = 0; k < 2; ++k) dst[n][k] = *(const PG8_LAS bf16x8*)(lds + PG8_SB(b, h) + boff + n * 2048 + k * 1024); } while (0)
; #define PG8_SCHED __builtin_amdgcn_sched_barrier(0)
; template <class Epi, class Sched, bool ALIGN_EPI = false, bool SP2 = false>
; __device__ __forceinline__ void gemm_phase(PG8_LAS unsigned char* lds, const Gemm g, const Sched& S, const Epi& E, const int wid_in) {
;     ...
;             const bool last = (t == nt - 2);
;             const char* a1 = cA + (size_t)(t + 1) * kstep;
;             const char* a2 = last ? nA : cA + (size_t)(t + 2) * kstep; const char* b2 = last ? nB : cB + (size_t)(t + 2) * kstep;
;             const char* a3 = a2 + kstep; const char* b3 = b2 + kstep;
;             if (last && has_next) S.a_ready(nxt);
;             if constexpr (SP2) {
;             PG8_LDB(B0, 0, 0); PG8_LDB(B1, 0, 1); PG8_SCHED; PG8_LDA(At, 0, 0); PG8_STAGE(PG8_SA(1, 1), a1 + hstepA, voffA);
.LBB0_484:
	s_add_u32 s0, s24, 0xfff80080
	s_addc_u32 s1, s25, -1
	s_add_i32 s49, 0, 0x10000
	s_cmp_eq_u32 s48, 28
	s_cselect_b32 s3, s19, s1
	s_cselect_b32 s2, s44, s0
	v_add_u32_e32 v150, s49, v152
	s_cselect_b32 s1, s17, s47
	s_cselect_b32 s0, s45, s46
	s_add_i32 s52, 0, 0x14000
	ds_read_b128 v[142:145], v150
	ds_read_b128 v[146:149], v150 offset:1024
	ds_read_b128 v[168:171], v150 offset:2048
	ds_read_b128 v[174:177], v150 offset:3072
	v_add_u32_e32 v150, s52, v152
	ds_read_b128 v[178:181], v150
	ds_read_b128 v[182:185], v150 offset:1024
	ds_read_b128 v[186:189], v150 offset:2048
	ds_read_b128 v[202:205], v150 offset:3072
	v_lshl_add_u64 v[150:151], s[24:25], 0, v[138:139]
	s_add_i32 m0, s35, 0xc000
	ds_read_b128 v[206:209], v167
	ds_read_b128 v[210:213], v167 offset:1024
	ds_read_b128 v[214:217], v167 offset:2048
	ds_read_b128 v[218:221], v167 offset:3072
	ds_read_b128 v[222:225], v167 offset:4096
	ds_read_b128 v[226:229], v167 offset:5120
	ds_read_b128 v[230:233], v167 offset:6144
	ds_read_b128 v[234:237], v167 offset:7168
	s_cmp_eq_u32 s100, 1
	s_cbranch_scc1 .Lrx_p6_skA
	global_load_lds_dwordx4 v[150:151], off
.Lrx_p6_skA:
	v_lshl_add_u64 v[150:151], s[24:25], 0, v[140:141]
	s_add_i32 m0, s35, 0xe000
	s_nop 0
	s_cmp_eq_u32 s100, 1
	s_cbranch_scc1 .Lrx_p6_skB
	global_load_lds_dwordx4 v[150:151], off

; #define PG8_STAGE(bufoff, gbase, voff) do { _Pragma("unroll") for (int _i = 0; _i < 2; ++_i) \
;         __builtin_amdgcn_global_load_lds((const unsigned*)((const char*)(gbase) + (voff)[_i]), (PG8_LAS unsigned*)(lds + (bufoff) + ldsw + _i * 8192), 16, 0, 0); } while (0)
; #define PG8_LDA(dst, b, h) do { _Pragma("unroll") for (int m = 0; m < 4; ++m) _Pragma("unroll") for (int k = 0; k < 2; ++k) dst[m][k] = *(const PG8_LAS bf16x8*)(lds + PG8_SA(b, h) + aoff + m * 2048 + k * 1024); } while (0)
; #define PG8_LDB(dst, b, h) do { _Pragma("unroll") for (int n = 0; n < 2; ++n) _Pragma("unroll") for (int k = 0; k < 2; ++k) dst[n][k] = *(const PG8_LAS bf16x8*)(lds + PG8_SB(b, h) + boff + n * 2048 + k * 1024); } while (0)
; #define PG8_MMA(ai, bj, At, Bt) do { __builtin_amdgcn_s_setprio(1); _Pragma("unroll") for (int m = 0; m < 4; ++m) _Pragma("unroll") for (int n = 0; n < 2; ++n) _Pragma("unroll") for (int k = 0; k < 2; ++k) \
;         acc[ai][bj][m][n] = __builtin_amdgcn_mfma_f32_16x16x32_bf16(Bt[n][k], At[m][k], acc[ai][bj][m][n], 0, 0, 0); __builtin_amdgcn_s_setprio(0); } while (0)
; #define PG8_WAIT_V(n) asm volatile("s_waitcnt vmcnt(" #n ")" ::: "memory")
; #define PG8_WAIT_L(n) asm volatile("s_waitcnt lgkmcnt(" #n ")" ::: "memory")
; #define PG8_BAR __builtin_amdgcn_s_barrier()
; #define PG8_SCHED __builtin_amdgcn_sched_barrier(0)
; template <class Epi, class Sched, bool ALIGN_EPI = false, bool SP2 = false>
; __device__ __forceinline__ void gemm_phase(PG8_LAS unsigned char* lds, const Gemm g, const Sched& S, const Epi& E, const int wid_in) {
;     ...
;             PG8_LDB(B0, 0, 0); PG8_LDB(B1, 0, 1); PG8_SCHED; PG8_LDA(At, 0, 0); PG8_STAGE(PG8_SA(1, 1), a1 + hstepA, voffA);
;             PG8_WAIT_V(8); PG8_WAIT_L(0); PG8_BAR; PG8_MMA(0, 0, At, B0); PG8_MMA(0, 1, At, B1); PG8_BAR; PG8_SCHED;
;             PG8_LDA(At, 0, 1); PG8_STAGE(PG8_SB(0, 0), b2, voffB); PG8_STAGE(PG8_SB(0, 1), b2 + hstep, voffB); PG8_STAGE(PG8_SA(0, 0), a2, voffA);
;             PG8_WAIT_V(8); PG8_WAIT_L(0); PG8_BAR; PG8_MMA(1, 0, At, B0); PG8_MMA(1, 1, At, B1); PG8_BAR; PG8_SCHED;
.Lrx_p6_wd_0:
	s_waitcnt lgkmcnt(0)
	s_setprio 1
	s_waitcnt lgkmcnt(0)
	v_mfma_f32_16x16x32_bf16 v[126:129], v[142:145], v[206:209], v[126:129]
	v_mfma_f32_16x16x32_bf16 v[122:125], v[168:171], v[206:209], v[122:125]
	s_barrier
	v_mfma_f32_16x16x32_bf16 v[110:113], v[142:145], v[214:217], v[110:113]
	v_mfma_f32_16x16x32_bf16 v[106:109], v[168:171], v[214:217], v[106:109]
	v_mfma_f32_16x16x32_bf16 v[94:97], v[142:145], v[222:225], v[94:97]
	v_mfma_f32_16x16x32_bf16 v[90:93], v[168:171], v[222:225], v[90:93]
	v_mfma_f32_16x16x32_bf16 v[78:81], v[142:145], v[230:233], v[78:81]
	v_mfma_f32_16x16x32_bf16 v[74:77], v[168:171], v[230:233], v[74:77]
	v_mfma_f32_16x16x32_bf16 v[126:129], v[146:149], v[210:213], v[126:129]
	v_mfma_f32_16x16x32_bf16 v[122:125], v[174:177], v[210:213], v[122:125]
	v_mfma_f32_16x16x32_bf16 v[110:113], v[146:149], v[218:221], v[110:113]
	v_mfma_f32_16x16x32_bf16 v[106:109], v[174:177], v[218:221], v[106:109]
	v_mfma_f32_16x16x32_bf16 v[94:97], v[146:149], v[226:229], v[94:97]
	v_mfma_f32_16x16x32_bf16 v[90:93], v[174:177], v[226:229], v[90:93]
	v_mfma_f32_16x16x32_bf16 v[78:81], v[146:149], v[234:237], v[78:81]
	v_mfma_f32_16x16x32_bf16 v[74:77], v[174:177], v[234:237], v[74:77]
	s_setprio 0
	s_setprio 1
	v_mfma_f32_16x16x32_bf16 v[118:121], v[178:181], v[206:209], v[118:121]
	v_mfma_f32_16x16x32_bf16 v[114:117], v[186:189], v[206:209], v[114:117]
	v_mfma_f32_16x16x32_bf16 v[102:105], v[178:181], v[214:217], v[102:105]
	v_mfma_f32_16x16x32_bf16 v[98:101], v[186:189], v[214:217], v[98:101]
	v_mfma_f32_16x16x32_bf16 v[86:89], v[178:181], v[222:225], v[86:89]
	v_mfma_f32_16x16x32_bf16 v[82:85], v[186:189], v[222:225], v[82:85]
	v_mfma_f32_16x16x32_bf16 v[70:73], v[178:181], v[230:233], v[70:73]
	v_mfma_f32_16x16x32_bf16 v[66:69], v[186:189], v[230:233], v[66:69]
	v_mfma_f32_16x16x32_bf16 v[118:121], v[182:185], v[210:213], v[118:121]
	v_mfma_f32_16x16x32_bf16 v[114:117], v[202:205], v[210:213], v[114:117]
	v_mfma_f32_16x16x32_bf16 v[102:105], v[182:185], v[218:221], v[102:105]
	v_mfma_f32_16x16x32_bf16 v[98:101], v[202:205], v[218:221], v[98:101]
	v_mfma_f32_16x16x32_bf16 v[86:89], v[182:185], v[226:229], v[86:89]
	v_mfma_f32_16x16x32_bf16 v[82:85], v[202:205], v[226:229], v[82:85]
	v_mfma_f32_16x16x32_bf16 v[70:73], v[182:185], v[234:237], v[70:73]
	v_mfma_f32_16x16x32_bf16 v[66:69], v[202:205], v[234:237], v[66:69]
	s_setprio 0
	s_barrier
	s_add_i32 s49, s49, s29
	v_lshl_add_u64 v[150:151], s[0:1], 0, v[134:135]
	s_mov_b32 m0, s49
	ds_read_b128 v[206:209], v167 offset:16384
	ds_read_b128 v[210:213], v167 offset:17408
	ds_read_b128 v[214:217], v167 offset:18432
	ds_read_b128 v[218:221], v167 offset:19456
	ds_read_b128 v[222:225], v167 offset:20480
	ds_read_b128 v[226:229], v167 offset:21504
	ds_read_b128 v[230:233], v167 offset:22528
	ds_read_b128 v[234:237], v167 offset:23552
	global_load_lds_dwordx4 v[150:151], off
	s_add_i32 m0, s49, 0x2000
	s_add_u32 s50, s0, 0x80000
	v_lshl_add_u64 v[190:191], s[0:1], 0, v[130:131]
	s_addc_u32 s51, s1, 0
	s_add_i32 s49, s52, s29
	global_load_lds_dwordx4 v[190:191], off
	v_lshl_add_u64 v[238:239], s[50:51], 0, v[134:135]
	s_mov_b32 m0, s49
	v_lshl_add_u64 v[240:241], s[2:3], 0, v[132:133]
	global_load_lds_dwordx4 v[238:239], off
	v_lshl_add_u64 v[238:239], s[50:51], 0, v[130:131]
	s_add_i32 m0, s49, 0x2000
	s_nop 0
	global_load_lds_dwordx4 v[238:239], off
	v_lshl_add_u64 v[238:239], s[2:3], 0, v[136:137]
	s_mov_b32 m0, s35
	s_nop 0
	global_load_lds_dwordx4 v[238:239], off
	s_mov_b32 m0, s36
	s_nop 0
	global_load_lds_dwordx4 v[240:241], off
	s_cmp_eq_u32 s100, 1
	s_cbranch_scc1 .Lrx_p6_w24_1
	s_waitcnt vmcnt(8)
	s_branch .Lrx_p6_wd_1

; #define PG8_STAGE(bufoff, gbase, voff) do { _Pragma("unroll") for (int _i = 0; _i < 2; ++_i) \
;         __builtin_amdgcn_global_load_lds((const unsigned*)((const char*)(gbase) + (voff)[_i]), (PG8_LAS unsigned*)(lds + (bufoff) + ldsw + _i * 8192), 16, 0, 0); } while (0)
; #define PG8_LDA(dst, b, h) do { _Pragma("unroll") for (int m = 0; m < 4; ++m) _Pragma("unroll") for (int k = 0; k < 2; ++k) dst[m][k] = *(const PG8_LAS bf16x8*)(lds + PG8_SA(b, h) + aoff + m * 2048 + k * 1024); } while (0)
; #define PG8_LDB(dst, b, h) do { _Pragma("unroll") for (int n = 0; n < 2; ++n) _Pragma("unroll") for (int k = 0; k < 2; ++k) dst[n][k] = *(const PG8_LAS bf16x8*)(lds + PG8_SB(b, h) + boff + n * 2048 + k * 1024); } while (0)
; #define PG8_MMA(ai, bj, At, Bt) do { __builtin_amdgcn_s_setprio(1); _Pragma("unroll") for (int m = 0; m < 4; ++m) _Pragma("unroll") for (int n = 0; n < 2; ++n) _Pragma("unroll") for (int k = 0; k < 2; ++k) \
;         acc[ai][bj][m][n] = __builtin_amdgcn_mfma_f32_16x16x32_bf16(Bt[n][k], At[m][k], acc[ai][bj][m][n], 0, 0, 0); __builtin_amdgcn_s_setprio(0); } while (0)
; #define PG8_WAIT_V(n) asm volatile("s_waitcnt vmcnt(" #n ")" ::: "memory")
; #define PG8_WAIT_L(n) asm volatile("s_waitcnt lgkmcnt(" #n ")" ::: "memory")
; #define PG8_BAR __builtin_amdgcn_s_barrier()
; #define PG8_SCHED __builtin_amdgcn_sched_barrier(0)
; template <class Epi, class Sched, bool ALIGN_EPI = false, bool SP2 = false>
; __device__ __forceinline__ void gemm_phase(PG8_LAS unsigned char* lds, const Gemm g, const Sched& S, const Epi& E, const int wid_in) {
;     ...
;             PG8_WAIT_V(8); PG8_WAIT_L(0); PG8_BAR; PG8_MMA(1, 0, At, B0); PG8_MMA(1, 1, At, B1); PG8_BAR; PG8_SCHED;
;             PG8_LDB(B0, 1, 0); PG8_LDB(B1, 1, 1); PG8_SCHED; PG8_LDA(At, 1, 0); PG8_STAGE(PG8_SA(0, 1), a2 + hstepA, voffA);
;             PG8_WAIT_V(8); PG8_WAIT_L(0); PG8_BAR; PG8_MMA(0, 0, At, B0); PG8_MMA(0, 1, At, B1); PG8_BAR; PG8_SCHED;
.Lrx_p6_wd_1:
	s_waitcnt lgkmcnt(0)
	s_setprio 1
	s_waitcnt lgkmcnt(0)
	v_mfma_f32_16x16x32_bf16 v[62:65], v[142:145], v[206:209], v[62:65]
	v_mfma_f32_16x16x32_bf16 v[58:61], v[168:171], v[206:209], v[58:61]
	s_barrier
	v_mfma_f32_16x16x32_bf16 v[46:49], v[142:145], v[214:217], v[46:49]
	v_mfma_f32_16x16x32_bf16 v[42:45], v[168:171], v[214:217], v[42:45]
	v_mfma_f32_16x16x32_bf16 v[30:33], v[142:145], v[222:225], v[30:33]
	v_mfma_f32_16x16x32_bf16 v[26:29], v[168:171], v[222:225], v[26:29]
	v_mfma_f32_16x16x32_bf16 v[14:17], v[142:145], v[230:233], v[14:17]
	v_mfma_f32_16x16x32_bf16 v[10:13], v[168:171], v[230:233], v[10:13]
	v_mfma_f32_16x16x32_bf16 v[62:65], v[146:149], v[210:213], v[62:65]
	v_mfma_f32_16x16x32_bf16 v[58:61], v[174:177], v[210:213], v[58:61]
	v_mfma_f32_16x16x32_bf16 v[46:49], v[146:149], v[218:221], v[46:49]
	v_mfma_f32_16x16x32_bf16 v[42:45], v[174:177], v[218:221], v[42:45]
	v_mfma_f32_16x16x32_bf16 v[30:33], v[146:149], v[226:229], v[30:33]
	v_mfma_f32_16x16x32_bf16 v[26:29], v[174:177], v[226:229], v[26:29]
	v_mfma_f32_16x16x32_bf16 v[14:17], v[146:149], v[234:237], v[14:17]
	v_mfma_f32_16x16x32_bf16 v[10:13], v[174:177], v[234:237], v[10:13]
	s_setprio 0
	s_setprio 1
	v_mfma_f32_16x16x32_bf16 v[54:57], v[178:181], v[206:209], v[54:57]
	v_mfma_f32_16x16x32_bf16 v[50:53], v[186:189], v[206:209], v[50:53]
	v_mfma_f32_16x16x32_bf16 v[38:41], v[178:181], v[214:217], v[38:41]
	v_mfma_f32_16x16x32_bf16 v[34:37], v[186:189], v[214:217], v[34:37]
	v_mfma_f32_16x16x32_bf16 v[22:25], v[178:181], v[222:225], v[22:25]
	v_mfma_f32_16x16x32_bf16 v[18:21], v[186:189], v[222:225], v[18:21]
	v_mfma_f32_16x16x32_bf16 v[6:9], v[178:181], v[230:233], v[6:9]
	v_mfma_f32_16x16x32_bf16 v[2:5], v[186:189], v[230:233], v[2:5]
	v_mfma_f32_16x16x32_bf16 v[54:57], v[182:185], v[210:213], v[54:57]
	v_mfma_f32_16x16x32_bf16 v[50:53], v[202:205], v[210:213], v[50:53]
	v_mfma_f32_16x16x32_bf16 v[38:41], v[182:185], v[218:221], v[38:41]
	v_mfma_f32_16x16x32_bf16 v[34:37], v[202:205], v[218:221], v[34:37]
	v_mfma_f32_16x16x32_bf16 v[22:25], v[182:185], v[226:229], v[22:25]
	v_mfma_f32_16x16x32_bf16 v[18:21], v[202:205], v[226:229], v[18:21]
	v_mfma_f32_16x16x32_bf16 v[6:9], v[182:185], v[234:237], v[6:9]
	v_mfma_f32_16x16x32_bf16 v[2:5], v[202:205], v[234:237], v[2:5]
	s_setprio 0
	s_barrier
	s_add_i32 s49, 0, 0x18000
	s_add_i32 s50, 0, 0x1c000
	v_add_u32_e32 v174, s49, v152
	v_add_u32_e32 v202, s50, v152
	ds_read_b128 v[142:145], v174
	ds_read_b128 v[146:149], v174 offset:1024
	ds_read_b128 v[168:171], v174 offset:2048
	ds_read_b128 v[174:177], v174 offset:3072
	ds_read_b128 v[178:181], v202
	ds_read_b128 v[182:185], v202 offset:1024
	ds_read_b128 v[186:189], v202 offset:2048
	ds_read_b128 v[202:205], v202 offset:3072
	s_add_u32 s2, s2, 0x80000
	s_addc_u32 s3, s3, 0
	s_mov_b32 m0, s37
	v_lshl_add_u64 v[242:243], s[2:3], 0, v[136:137]
	ds_read_b128 v[206:209], v167 offset:32768
	ds_read_b128 v[210:213], v167 offset:33792
	ds_read_b128 v[214:217], v167 offset:34816
	ds_read_b128 v[218:221], v167 offset:35840
	ds_read_b128 v[222:225], v167 offset:36864
	ds_read_b128 v[226:229], v167 offset:37888
	ds_read_b128 v[230:233], v167 offset:38912
	ds_read_b128 v[234:237], v167 offset:39936
	global_load_lds_dwordx4 v[242:243], off
	v_lshl_add_u64 v[242:243], s[2:3], 0, v[132:133]
	s_mov_b32 m0, s38
	s_nop 0
	global_load_lds_dwordx4 v[242:243], off
	s_cmp_eq_u32 s100, 1
	s_cbranch_scc1 .Lrx_p6_w24_2
	s_waitcnt vmcnt(8)
	s_branch .Lrx_p6_wd_2

; #define PG8_STAGE(bufoff, gbase, voff) do { _Pragma("unroll") for (int _i = 0; _i < 2; ++_i) \
;         __builtin_amdgcn_global_load_lds((const unsigned*)((const char*)(gbase) + (voff)[_i]), (PG8_LAS unsigned*)(lds + (bufoff) + ldsw + _i * 8192), 16, 0, 0); } while (0)
; #define PG8_LDA(dst, b, h) do { _Pragma("unroll") for (int m = 0; m < 4; ++m) _Pragma("unroll") for (int k = 0; k < 2; ++k) dst[m][k] = *(const PG8_LAS bf16x8*)(lds + PG8_SA(b, h) + aoff + m * 2048 + k * 1024); } while (0)
; #define PG8_MMA(ai, bj, At, Bt) do { __builtin_amdgcn_s_setprio(1); _Pragma("unroll") for (int m = 0; m < 4; ++m) _Pragma("unroll") for (int n = 0; n < 2; ++n) _Pragma("unroll") for (int k = 0; k < 2; ++k) \
;         acc[ai][bj][m][n] = __builtin_amdgcn_mfma_f32_16x16x32_bf16(Bt[n][k], At[m][k], acc[ai][bj][m][n], 0, 0, 0); __builtin_amdgcn_s_setprio(0); } while (0)
; #define PG8_WAIT_V(n) asm volatile("s_waitcnt vmcnt(" #n ")" ::: "memory")
; #define PG8_WAIT_L(n) asm volatile("s_waitcnt lgkmcnt(" #n ")" ::: "memory")
; #define PG8_BAR __builtin_amdgcn_s_barrier()
; #define PG8_SCHED __builtin_amdgcn_sched_barrier(0)
; template <class Epi, class Sched, bool ALIGN_EPI = false, bool SP2 = false>
; __device__ __forceinline__ void gemm_phase(PG8_LAS unsigned char* lds, const Gemm g, const Sched& S, const Epi& E, const int wid_in) {
;     ...
;             PG8_WAIT_V(8); PG8_WAIT_L(0); PG8_BAR; PG8_MMA(0, 0, At, B0); PG8_MMA(0, 1, At, B1); PG8_BAR; PG8_SCHED;
;             PG8_LDA(At, 1, 1); PG8_STAGE(PG8_SB(1, 0), b3, voffB); PG8_STAGE(PG8_SB(1, 1), b3 + hstep, voffB); PG8_STAGE(PG8_SA(1, 0), a3, voffA);
;             PG8_WAIT_V(8); PG8_WAIT_L(0); PG8_BAR; PG8_MMA(1, 0, At, B0); PG8_MMA(1, 1, At, B1); PG8_BAR; PG8_SCHED;
.Lrx_p6_wd_2:
	s_waitcnt lgkmcnt(0)
	s_setprio 1
	s_waitcnt lgkmcnt(0)
	v_mfma_f32_16x16x32_bf16 v[126:129], v[142:145], v[206:209], v[126:129]
	v_mfma_f32_16x16x32_bf16 v[122:125], v[168:171], v[206:209], v[122:125]
	s_barrier
	v_mfma_f32_16x16x32_bf16 v[110:113], v[142:145], v[214:217], v[110:113]
	v_mfma_f32_16x16x32_bf16 v[106:109], v[168:171], v[214:217], v[106:109]
	v_mfma_f32_16x16x32_bf16 v[94:97], v[142:145], v[222:225], v[94:97]
	v_mfma_f32_16x16x32_bf16 v[90:93], v[168:171], v[222:225], v[90:93]
	v_mfma_f32_16x16x32_bf16 v[78:81], v[142:145], v[230:233], v[78:81]
	v_mfma_f32_16x16x32_bf16 v[74:77], v[168:171], v[230:233], v[74:77]
	v_mfma_f32_16x16x32_bf16 v[126:129], v[146:149], v[210:213], v[126:129]
	v_mfma_f32_16x16x32_bf16 v[122:125], v[174:177], v[210:213], v[122:125]
	v_mfma_f32_16x16x32_bf16 v[110:113], v[146:149], v[218:221], v[110:113]
	v_mfma_f32_16x16x32_bf16 v[106:109], v[174:177], v[218:221], v[106:109]
	v_mfma_f32_16x16x32_bf16 v[94:97], v[146:149], v[226:229], v[94:97]
	v_mfma_f32_16x16x32_bf16 v[90:93], v[174:177], v[226:229], v[90:93]
	v_mfma_f32_16x16x32_bf16 v[78:81], v[146:149], v[234:237], v[78:81]
	v_mfma_f32_16x16x32_bf16 v[74:77], v[174:177], v[234:237], v[74:77]
	s_setprio 0
	s_setprio 1
	v_mfma_f32_16x16x32_bf16 v[118:121], v[178:181], v[206:209], v[118:121]
	v_mfma_f32_16x16x32_bf16 v[114:117], v[186:189], v[206:209], v[114:117]
	v_mfma_f32_16x16x32_bf16 v[102:105], v[178:181], v[214:217], v[102:105]
	v_mfma_f32_16x16x32_bf16 v[98:101], v[186:189], v[214:217], v[98:101]
	v_mfma_f32_16x16x32_bf16 v[86:89], v[178:181], v[222:225], v[86:89]
	v_mfma_f32_16x16x32_bf16 v[82:85], v[186:189], v[222:225], v[82:85]
	v_mfma_f32_16x16x32_bf16 v[70:73], v[178:181], v[230:233], v[70:73]
	v_mfma_f32_16x16x32_bf16 v[66:69], v[186:189], v[230:233], v[66:69]
	v_mfma_f32_16x16x32_bf16 v[118:121], v[182:185], v[210:213], v[118:121]
	v_mfma_f32_16x16x32_bf16 v[114:117], v[202:205], v[210:213], v[114:117]
	v_mfma_f32_16x16x32_bf16 v[102:105], v[182:185], v[218:221], v[102:105]
	v_mfma_f32_16x16x32_bf16 v[98:101], v[202:205], v[218:221], v[98:101]
	v_mfma_f32_16x16x32_bf16 v[86:89], v[182:185], v[226:229], v[86:89]
	v_mfma_f32_16x16x32_bf16 v[82:85], v[202:205], v[226:229], v[82:85]
	v_mfma_f32_16x16x32_bf16 v[70:73], v[182:185], v[234:237], v[70:73]
	v_mfma_f32_16x16x32_bf16 v[66:69], v[202:205], v[234:237], v[66:69]
	s_setprio 0
	s_barrier
	s_add_i32 s2, s49, s29
	v_lshl_add_u64 v[150:151], v[150:151], 0, s[98:99]
	s_mov_b32 m0, s2
	ds_read_b128 v[206:209], v167 offset:49152
	ds_read_b128 v[210:213], v167 offset:50176
	ds_read_b128 v[214:217], v167 offset:51200
	ds_read_b128 v[218:221], v167 offset:52224
	ds_read_b128 v[222:225], v167 offset:53248
	ds_read_b128 v[226:229], v167 offset:54272
	ds_read_b128 v[230:233], v167 offset:55296
	ds_read_b128 v[234:237], v167 offset:56320
	global_load_lds_dwordx4 v[150:151], off
	s_add_i32 m0, s2, 0x2000
	s_add_u32 s0, s0, 0x80080
	v_lshl_add_u64 v[150:151], v[190:191], 0, s[98:99]
	s_addc_u32 s1, s1, 0
	s_add_i32 s2, s50, s29
	global_load_lds_dwordx4 v[150:151], off
	v_lshl_add_u64 v[150:151], s[0:1], 0, v[134:135]
	s_mov_b32 m0, s2
	s_nop 0
	global_load_lds_dwordx4 v[150:151], off
	v_lshl_add_u64 v[150:151], s[0:1], 0, v[130:131]
	s_add_i32 m0, s2, 0x2000
	s_nop 0
	global_load_lds_dwordx4 v[150:151], off
	v_lshl_add_u64 v[150:151], v[238:239], 0, s[98:99]
	s_mov_b32 m0, s39
	s_nop 0
	global_load_lds_dwordx4 v[150:151], off
	v_lshl_add_u64 v[150:151], v[240:241], 0, s[98:99]
	s_mov_b32 m0, s40
	s_nop 0
	global_load_lds_dwordx4 v[150:151], off
	s_waitcnt vmcnt(8)
	s_waitcnt lgkmcnt(0)
	s_setprio 1
	s_waitcnt lgkmcnt(0)
	v_mfma_f32_16x16x32_bf16 v[62:65], v[142:145], v[206:209], v[62:65]
	v_mfma_f32_16x16x32_bf16 v[58:61], v[168:171], v[206:209], v[58:61]
	s_barrier
	v_mfma_f32_16x16x32_bf16 v[46:49], v[142:145], v[214:217], v[46:49]
	v_mfma_f32_16x16x32_bf16 v[42:45], v[168:171], v[214:217], v[42:45]
	v_mfma_f32_16x16x32_bf16 v[30:33], v[142:145], v[222:225], v[30:33]
	v_mfma_f32_16x16x32_bf16 v[26:29], v[168:171], v[222:225], v[26:29]
	v_mfma_f32_16x16x32_bf16 v[14:17], v[142:145], v[230:233], v[14:17]
	v_mfma_f32_16x16x32_bf16 v[10:13], v[168:171], v[230:233], v[10:13]
	v_mfma_f32_16x16x32_bf16 v[62:65], v[146:149], v[210:213], v[62:65]
	v_mfma_f32_16x16x32_bf16 v[58:61], v[174:177], v[210:213], v[58:61]
	v_mfma_f32_16x16x32_bf16 v[46:49], v[146:149], v[218:221], v[46:49]
	v_mfma_f32_16x16x32_bf16 v[42:45], v[174:177], v[218:221], v[42:45]
	v_mfma_f32_16x16x32_bf16 v[30:33], v[146:149], v[226:229], v[30:33]
	v_mfma_f32_16x16x32_bf16 v[26:29], v[174:177], v[226:229], v[26:29]
	v_mfma_f32_16x16x32_bf16 v[14:17], v[146:149], v[234:237], v[14:17]
	v_mfma_f32_16x16x32_bf16 v[10:13], v[174:177], v[234:237], v[10:13]
	s_setprio 0
	s_setprio 1
	v_mfma_f32_16x16x32_bf16 v[54:57], v[178:181], v[206:209], v[54:57]
	v_mfma_f32_16x16x32_bf16 v[50:53], v[186:189], v[206:209], v[50:53]
	v_mfma_f32_16x16x32_bf16 v[38:41], v[178:181], v[214:217], v[38:41]
	v_mfma_f32_16x16x32_bf16 v[34:37], v[186:189], v[214:217], v[34:37]
	v_mfma_f32_16x16x32_bf16 v[22:25], v[178:181], v[222:225], v[22:25]
	v_mfma_f32_16x16x32_bf16 v[18:21], v[186:189], v[222:225], v[18:21]
	v_mfma_f32_16x16x32_bf16 v[6:9], v[178:181], v[230:233], v[6:9]
	v_mfma_f32_16x16x32_bf16 v[2:5], v[186:189], v[230:233], v[2:5]
	v_mfma_f32_16x16x32_bf16 v[54:57], v[182:185], v[210:213], v[54:57]
	v_mfma_f32_16x16x32_bf16 v[50:53], v[202:205], v[210:213], v[50:53]
	v_mfma_f32_16x16x32_bf16 v[38:41], v[182:185], v[218:221], v[38:41]
	v_mfma_f32_16x16x32_bf16 v[34:37], v[202:205], v[218:221], v[34:37]
	v_mfma_f32_16x16x32_bf16 v[22:25], v[182:185], v[226:229], v[22:25]
	v_mfma_f32_16x16x32_bf16 v[18:21], v[202:205], v[226:229], v[18:21]
	v_mfma_f32_16x16x32_bf16 v[6:9], v[182:185], v[234:237], v[6:9]
	v_mfma_f32_16x16x32_bf16 v[2:5], v[202:205], v[234:237], v[2:5]
	s_setprio 0
	s_barrier
	s_mov_b32 s100, 0
	s_add_i32 s48, s48, 2
	s_add_u32 s24, s24, 0x100
	s_addc_u32 s25, s25, 0
	s_add_u32 s46, s46, 0x100
	s_addc_u32 s47, s47, 0
	s_cmp_gt_u32 s48, 29
	s_cbranch_scc0 .LBB0_484
	s_and_b64 vcc, exec, s[14:15]
	s_cbranch_vccz .LBB0_487
	s_barrier
; __device__ __forceinline__ unsigned cvt_pk_bf16(float lo, float hi) { unsigned r; asm volatile("v_cvt_pk_bf16_f32 %0, %1, %2" : "=v"(r) : "v"(lo), "v"(hi)); return r; }
; #define EPI_FENCE() asm volatile("" ::: "memory")
; __device__ __forceinline__ void load_rs(float (&rs)[8], const RsTable& T, int pm, int lrow0) {
;     const int k = pm == T.pm[0] ? 0 : (pm == T.pm[1] ? 1 : (pm == T.pm[2] ? 2 : 3));
; #pragma unroll
;     for (int i = 0; i < 8; ++i) rs[i] = T.tab[k * 256 + lrow0 + (i >> 2) * HALF + (i & 3) * 16];
;     __device__ __forceinline__ void operator()(const f32x4 (&acc)[2][2][4][2], const Unit& u, int wr, int wc, int fr, int fq) const {
;         const int row0 = u.pm * BM + wr * 64 + fr; const int col0 = u.pn * BM + wc * 32 + 8 * fq;
;         float rs[8]; load_rs(rs, rst, u.pm, wr * 64 + fr);
;         EPI_FENCE();
; #pragma unroll
;         for (int i = 0; i < 8; ++i) { const int ai = i >> 2, m = i & 3; bf16_t* rowp = O + (size_t)(row0 + ai * HALF + m * 16) * ldc + col0;
; #pragma unroll
;             for (int bj = 0; bj < 2; ++bj) { f32x4 v0 = acc[ai][bj][m][0] * rs[i], v1 = acc[ai][bj][m][1] * rs[i];
; #pragma unroll
;                 for (int e = 0; e < 4; ++e) { const float a = fmaxf(v0[e], 0.f), b = fmaxf(v1[e], 0.f); v0[e] = a * a; v1[e] = b * b; }
;                 u32x4 w; w.x = cvt_pk_bf16(v0[0], v0[1]); w.y = cvt_pk_bf16(v0[2], v0[3]); w.z = cvt_pk_bf16(v1[0], v1[1]); w.w = cvt_pk_bf16(v1[2], v1[3]);
;                 *(u32x4*)(rowp + bj * HALF) = w; } }
.LBB0_487:
	s_add_u32 s100, s44, 0x80080
	s_addc_u32 s101, s19, 0
	s_add_i32 m0, s35, 0xc000
	v_lshl_add_u64 v[150:151], s[100:101], 0, v[138:139]
	global_load_lds_dwordx4 v[150:151], off
	s_add_i32 m0, s35, 0xe000
	v_lshl_add_u64 v[150:151], s[100:101], 0, v[140:141]
	global_load_lds_dwordx4 v[150:151], off
	s_mov_b32 s100, 1
	s_cmp_eq_u32 s43, s28
	s_cselect_b32 s0, 0x200, s56
	s_cmp_lg_u32 s43, s27
	s_cselect_b32 s0, s0, 0x100
	s_cmp_lg_u32 s43, s26
	s_cselect_b32 s0, s0, 0
	v_lshl_add_u32 v143, s0, 2, v166
	ds_read2_b32 v[168:169], v143 offset1:16
	ds_read2_b32 v[170:171], v143 offset0:32 offset1:48
	ds_read2_b32 v[148:149], v143 offset0:128 offset1:144
	ds_read2_b32 v[144:145], v143 offset0:160 offset1:176
	v_lshl_add_u32 v142, s43, 8, v1
	s_waitcnt lgkmcnt(0)
	v_pk_mul_f32 v[122:123], v[122:123], v[168:169] op_sel_hi:[1,0]
	v_lshl_add_u32 v146, s42, 8, v153
	v_ashrrev_i32_e32 v143, 31, v142
	v_pk_mul_f32 v[126:127], v[126:127], v[168:169] op_sel_hi:[1,0]
	v_pk_mul_f32 v[124:125], v[124:125], v[168:169] op_sel_hi:[1,0]
	v_max_f32_e32 v122, 0, v122
	v_ashrrev_i32_e32 v147, 31, v146
	v_lshlrev_b64 v[150:151], 14, v[142:143]
	v_pk_mul_f32 v[128:129], v[128:129], v[168:169] op_sel_hi:[1,0]
	v_mul_f32_e32 v143, v122, v122
	v_max_f32_e32 v122, 0, v127
	v_max_f32_e32 v123, 0, v123
	v_max_f32_e32 v124, 0, v124
	v_lshl_add_u64 v[150:151], s[12:13], 0, v[150:151]
	v_lshlrev_b64 v[146:147], 1, v[146:147]
	v_max_f32_e32 v126, 0, v126
	v_mul_f32_e32 v122, v122, v122
	v_mul_f32_e32 v127, v123, v123
	v_max_f32_e32 v123, 0, v128
	v_mul_f32_e32 v128, v124, v124
	v_max_f32_e32 v124, 0, v129
	v_max_f32_e32 v125, 0, v125
	v_pk_mul_f32 v[116:117], v[116:117], v[168:169] op_sel_hi:[1,0]
	v_pk_mul_f32 v[114:115], v[114:115], v[168:169] op_sel_hi:[1,0]
	v_lshl_add_u64 v[150:151], v[150:151], 0, v[146:147]
	v_mul_f32_e32 v126, v126, v126
	v_mul_f32_e32 v123, v123, v123
	v_mul_f32_e32 v124, v124, v124
	v_mul_f32_e32 v125, v125, v125
	v_cvt_pk_bf16_f32 v122, v126, v122
	v_pk_mul_f32 v[120:121], v[120:121], v[168:169] op_sel_hi:[1,0]
	v_pk_mul_f32 v[118:119], v[118:119], v[168:169] op_sel_hi:[1,0]
	v_max_f32_e32 v114, 0, v114
	v_max_f32_e32 v115, 0, v115
	v_max_f32_e32 v116, 0, v116
	v_cvt_pk_bf16_f32 v123, v123, v124
	v_cvt_pk_bf16_f32 v124, v143, v127
	v_cvt_pk_bf16_f32 v125, v128, v125
	ds_bpermute_b32 v174, v255, v150
	ds_bpermute_b32 v175, v255, v151
	ds_bpermute_b32 v176, v255, v122
	ds_bpermute_b32 v177, v255, v123
	ds_bpermute_b32 v178, v255, v124
	ds_bpermute_b32 v179, v255, v125
	s_waitcnt lgkmcnt(0)
	global_store_dwordx4 v[174:175], v[176:179], off
	v_max_f32_e32 v118, 0, v118
	v_max_f32_e32 v117, 0, v117
	v_mul_f32_e32 v122, v114, v114
	v_max_f32_e32 v114, 0, v119
	v_mul_f32_e32 v119, v115, v115
	v_max_f32_e32 v115, 0, v120
	v_mul_f32_e32 v120, v116, v116
	v_max_f32_e32 v116, 0, v121
	v_mul_f32_e32 v114, v114, v114
	v_mul_f32_e32 v115, v115, v115
	v_mul_f32_e32 v116, v116, v116
	v_mul_f32_e32 v118, v118, v118
	v_mul_f32_e32 v117, v117, v117
	v_cvt_pk_bf16_f32 v114, v118, v114
	v_cvt_pk_bf16_f32 v115, v115, v116
	v_cvt_pk_bf16_f32 v116, v122, v119
	v_cvt_pk_bf16_f32 v117, v120, v117
	ds_bpermute_b32 v118, v255, v150
	ds_bpermute_b32 v119, v255, v151
	ds_bpermute_b32 v120, v255, v114
	ds_bpermute_b32 v121, v255, v115
	ds_bpermute_b32 v122, v255, v116
	ds_bpermute_b32 v123, v255, v117
	s_waitcnt lgkmcnt(0)
	global_store_dwordx4 v[118:119], v[120:123], off offset:256
	v_pk_mul_f32 v[90:91], v[90:91], v[170:171] op_sel_hi:[1,0]
	v_pk_mul_f32 v[94:95], v[94:95], v[170:171] op_sel_hi:[1,0]
	v_mov_b32_e32 v116, v169
	v_or_b32_e32 v114, 16, v142
	v_pk_mul_f32 v[106:107], v[106:107], v[116:117] op_sel_hi:[1,0]
	v_ashrrev_i32_e32 v115, 31, v114
	v_pk_mul_f32 v[110:111], v[110:111], v[116:117] op_sel_hi:[1,0]
	v_pk_mul_f32 v[108:109], v[108:109], v[116:117] op_sel_hi:[1,0]
	v_max_f32_e32 v106, 0, v106
	v_lshlrev_b64 v[114:115], 14, v[114:115]
	v_pk_mul_f32 v[112:113], v[112:113], v[116:117] op_sel_hi:[1,0]
	v_mul_f32_e32 v117, v106, v106
	v_max_f32_e32 v106, 0, v111
	v_max_f32_e32 v107, 0, v107
	v_max_f32_e32 v108, 0, v108
	v_lshl_add_u64 v[114:115], s[12:13], 0, v[114:115]
	v_max_f32_e32 v110, 0, v110
	v_mul_f32_e32 v106, v106, v106
	v_mul_f32_e32 v111, v107, v107
	v_max_f32_e32 v107, 0, v112
	v_mul_f32_e32 v112, v108, v108
	v_max_f32_e32 v108, 0, v113
	v_max_f32_e32 v109, 0, v109
	v_pk_mul_f32 v[98:99], v[98:99], v[116:117] op_sel_hi:[1,0]
	v_lshl_add_u64 v[114:115], v[114:115], 0, v[146:147]
	v_mul_f32_e32 v110, v110, v110
	v_mul_f32_e32 v107, v107, v107
	v_mul_f32_e32 v108, v108, v108
	v_mul_f32_e32 v109, v109, v109
	v_cvt_pk_bf16_f32 v106, v110, v106
	v_pk_mul_f32 v[102:103], v[102:103], v[116:117] op_sel_hi:[1,0]
	v_pk_mul_f32 v[100:101], v[100:101], v[116:117] op_sel_hi:[1,0]
	v_max_f32_e32 v98, 0, v98
	v_cvt_pk_bf16_f32 v107, v107, v108
	v_cvt_pk_bf16_f32 v108, v117, v111
	v_cvt_pk_bf16_f32 v109, v112, v109
	ds_bpermute_b32 v118, v255, v114
	ds_bpermute_b32 v119, v255, v115
	ds_bpermute_b32 v120, v255, v106
	ds_bpermute_b32 v121, v255, v107
	ds_bpermute_b32 v122, v255, v108
	ds_bpermute_b32 v123, v255, v109
	s_waitcnt lgkmcnt(0)
	global_store_dwordx4 v[118:119], v[120:123], off
	v_pk_mul_f32 v[104:105], v[104:105], v[116:117] op_sel_hi:[1,0]
	v_max_f32_e32 v99, 0, v99
	v_mul_f32_e32 v106, v98, v98
	v_max_f32_e32 v98, 0, v103
	v_max_f32_e32 v100, 0, v100
	v_max_f32_e32 v102, 0, v102
	v_mul_f32_e32 v98, v98, v98
	v_mul_f32_e32 v103, v99, v99
	v_max_f32_e32 v99, 0, v104
	v_mul_f32_e32 v104, v100, v100
	v_max_f32_e32 v100, 0, v105
	v_max_f32_e32 v101, 0, v101
	v_mul_f32_e32 v102, v102, v102
	v_mul_f32_e32 v99, v99, v99
	v_mul_f32_e32 v100, v100, v100
	v_mul_f32_e32 v101, v101, v101
	v_cvt_pk_bf16_f32 v98, v102, v98
	v_cvt_pk_bf16_f32 v99, v99, v100
	v_cvt_pk_bf16_f32 v100, v106, v103
	v_cvt_pk_bf16_f32 v101, v104, v101
	ds_bpermute_b32 v102, v255, v114
	ds_bpermute_b32 v103, v255, v115
	ds_bpermute_b32 v104, v255, v98
	ds_bpermute_b32 v105, v255, v99
	ds_bpermute_b32 v106, v255, v100
	ds_bpermute_b32 v107, v255, v101
	s_waitcnt lgkmcnt(0)
; __device__ __forceinline__ unsigned cvt_pk_bf16(float lo, float hi) { unsigned r; asm volatile("v_cvt_pk_bf16_f32 %0, %1, %2" : "=v"(r) : "v"(lo), "v"(hi)); return r; }
;     __device__ __forceinline__ void operator()(const f32x4 (&acc)[2][2][4][2], const Unit& u, int wr, int wc, int fr, int fq) const {
;     ...
;         for (int i = 0; i < 8; ++i) { const int ai = i >> 2, m = i & 3; bf16_t* rowp = O + (size_t)(row0 + ai * HALF + m * 16) * ldc + col0;
; #pragma unroll
;             for (int bj = 0; bj < 2; ++bj) { f32x4 v0 = acc[ai][bj][m][0] * rs[i], v1 = acc[ai][bj][m][1] * rs[i];
; #pragma unroll
;                 for (int e = 0; e < 4; ++e) { const float a = fmaxf(v0[e], 0.f), b = fmaxf(v1[e], 0.f); v0[e] = a * a; v1[e] = b * b; }
;                 u32x4 w; w.x = cvt_pk_bf16(v0[0], v0[1]); w.y = cvt_pk_bf16(v0[2], v0[3]); w.z = cvt_pk_bf16(v1[0], v1[1]); w.w = cvt_pk_bf16(v1[2], v1[3]);
;                 *(u32x4*)(rowp + bj * HALF) = w; } }
	global_store_dwordx4 v[102:103], v[104:107], off offset:256
	v_pk_mul_f32 v[92:93], v[92:93], v[170:171] op_sel_hi:[1,0]
	v_max_f32_e32 v90, 0, v90
	v_or_b32_e32 v98, 32, v142
	v_ashrrev_i32_e32 v99, 31, v98
	v_lshlrev_b64 v[98:99], 14, v[98:99]
	v_pk_mul_f32 v[96:97], v[96:97], v[170:171] op_sel_hi:[1,0]
	v_mul_f32_e32 v100, v90, v90
	v_max_f32_e32 v90, 0, v95
	v_max_f32_e32 v91, 0, v91
	v_max_f32_e32 v92, 0, v92
	v_lshl_add_u64 v[98:99], s[12:13], 0, v[98:99]
	v_max_f32_e32 v94, 0, v94
	v_mul_f32_e32 v90, v90, v90
	v_mul_f32_e32 v95, v91, v91
	v_max_f32_e32 v91, 0, v96
	v_mul_f32_e32 v96, v92, v92
	v_max_f32_e32 v92, 0, v97
	v_max_f32_e32 v93, 0, v93
	v_pk_mul_f32 v[84:85], v[84:85], v[170:171] op_sel_hi:[1,0]
	v_pk_mul_f32 v[82:83], v[82:83], v[170:171] op_sel_hi:[1,0]
	v_lshl_add_u64 v[98:99], v[98:99], 0, v[146:147]
	v_mul_f32_e32 v94, v94, v94
	v_mul_f32_e32 v91, v91, v91
	v_mul_f32_e32 v92, v92, v92
	v_mul_f32_e32 v93, v93, v93
	v_cvt_pk_bf16_f32 v90, v94, v90
	v_pk_mul_f32 v[88:89], v[88:89], v[170:171] op_sel_hi:[1,0]
	v_pk_mul_f32 v[86:87], v[86:87], v[170:171] op_sel_hi:[1,0]
	v_max_f32_e32 v82, 0, v82
	v_max_f32_e32 v83, 0, v83
	v_max_f32_e32 v84, 0, v84
	v_cvt_pk_bf16_f32 v91, v91, v92
	v_cvt_pk_bf16_f32 v92, v100, v95
	v_cvt_pk_bf16_f32 v93, v96, v93
	ds_bpermute_b32 v100, v255, v98
	ds_bpermute_b32 v101, v255, v99
	ds_bpermute_b32 v102, v255, v90
	ds_bpermute_b32 v103, v255, v91
	ds_bpermute_b32 v104, v255, v92
	ds_bpermute_b32 v105, v255, v93
	s_waitcnt lgkmcnt(0)
	global_store_dwordx4 v[100:101], v[102:105], off
	v_max_f32_e32 v86, 0, v86
	v_max_f32_e32 v85, 0, v85
	v_mul_f32_e32 v90, v82, v82
	v_max_f32_e32 v82, 0, v87
	v_mul_f32_e32 v87, v83, v83
	v_max_f32_e32 v83, 0, v88
	v_mul_f32_e32 v88, v84, v84
	v_max_f32_e32 v84, 0, v89
	v_mul_f32_e32 v82, v82, v82
	v_mul_f32_e32 v83, v83, v83
	v_mul_f32_e32 v84, v84, v84
	v_mul_f32_e32 v86, v86, v86
	v_mul_f32_e32 v85, v85, v85
	v_cvt_pk_bf16_f32 v82, v86, v82
	v_cvt_pk_bf16_f32 v83, v83, v84
	v_cvt_pk_bf16_f32 v84, v90, v87
	v_cvt_pk_bf16_f32 v85, v88, v85
	ds_bpermute_b32 v86, v255, v98
	ds_bpermute_b32 v87, v255, v99
	ds_bpermute_b32 v88, v255, v82
	ds_bpermute_b32 v89, v255, v83
	ds_bpermute_b32 v90, v255, v84
	ds_bpermute_b32 v91, v255, v85
	s_waitcnt lgkmcnt(0)
	global_store_dwordx4 v[86:87], v[88:91], off offset:256
	v_pk_mul_f32 v[58:59], v[58:59], v[148:149] op_sel_hi:[1,0]
	v_pk_mul_f32 v[62:63], v[62:63], v[148:149] op_sel_hi:[1,0]
	v_mov_b32_e32 v84, v171
	v_or_b32_e32 v82, 48, v142
	v_pk_mul_f32 v[74:75], v[74:75], v[84:85] op_sel_hi:[1,0]
	v_ashrrev_i32_e32 v83, 31, v82
	v_pk_mul_f32 v[78:79], v[78:79], v[84:85] op_sel_hi:[1,0]
	v_pk_mul_f32 v[76:77], v[76:77], v[84:85] op_sel_hi:[1,0]
	v_max_f32_e32 v74, 0, v74
	v_lshlrev_b64 v[82:83], 14, v[82:83]
	v_pk_mul_f32 v[80:81], v[80:81], v[84:85] op_sel_hi:[1,0]
	v_mul_f32_e32 v85, v74, v74
	v_max_f32_e32 v74, 0, v79
	v_max_f32_e32 v75, 0, v75
	v_max_f32_e32 v76, 0, v76
	v_lshl_add_u64 v[82:83], s[12:13], 0, v[82:83]
	v_max_f32_e32 v78, 0, v78
	v_mul_f32_e32 v74, v74, v74
	v_mul_f32_e32 v79, v75, v75
	v_max_f32_e32 v75, 0, v80
	v_mul_f32_e32 v80, v76, v76
	v_max_f32_e32 v76, 0, v81
	v_max_f32_e32 v77, 0, v77
	v_pk_mul_f32 v[68:69], v[68:69], v[84:85] op_sel_hi:[1,0]
	v_pk_mul_f32 v[66:67], v[66:67], v[84:85] op_sel_hi:[1,0]
	v_lshl_add_u64 v[82:83], v[82:83], 0, v[146:147]
	v_mul_f32_e32 v78, v78, v78
	v_mul_f32_e32 v75, v75, v75
	v_mul_f32_e32 v76, v76, v76
	v_mul_f32_e32 v77, v77, v77
	v_cvt_pk_bf16_f32 v74, v78, v74
	v_pk_mul_f32 v[72:73], v[72:73], v[84:85] op_sel_hi:[1,0]
	v_pk_mul_f32 v[70:71], v[70:71], v[84:85] op_sel_hi:[1,0]
	v_max_f32_e32 v66, 0, v66
	v_max_f32_e32 v67, 0, v67
	v_max_f32_e32 v68, 0, v68
	v_cvt_pk_bf16_f32 v75, v75, v76
	v_cvt_pk_bf16_f32 v76, v85, v79
	v_cvt_pk_bf16_f32 v77, v80, v77
	ds_bpermute_b32 v84, v255, v82
	ds_bpermute_b32 v85, v255, v83
	ds_bpermute_b32 v86, v255, v74
	ds_bpermute_b32 v87, v255, v75
	ds_bpermute_b32 v88, v255, v76
	ds_bpermute_b32 v89, v255, v77
	s_waitcnt lgkmcnt(0)
	global_store_dwordx4 v[84:85], v[86:89], off
	v_max_f32_e32 v70, 0, v70
	v_max_f32_e32 v69, 0, v69
	v_mul_f32_e32 v74, v66, v66
	v_max_f32_e32 v66, 0, v71
	v_mul_f32_e32 v71, v67, v67
	v_max_f32_e32 v67, 0, v72
	v_mul_f32_e32 v72, v68, v68
	v_max_f32_e32 v68, 0, v73
	v_mul_f32_e32 v66, v66, v66
	v_mul_f32_e32 v67, v67, v67
	v_mul_f32_e32 v68, v68, v68
	v_mul_f32_e32 v70, v70, v70
	v_mul_f32_e32 v69, v69, v69
	v_cvt_pk_bf16_f32 v66, v70, v66
	v_cvt_pk_bf16_f32 v67, v67, v68
	v_cvt_pk_bf16_f32 v68, v74, v71
	v_pk_mul_f32 v[60:61], v[60:61], v[148:149] op_sel_hi:[1,0]
	v_max_f32_e32 v58, 0, v58
	v_cvt_pk_bf16_f32 v69, v72, v69
	ds_bpermute_b32 v70, v255, v82
	ds_bpermute_b32 v71, v255, v83
	ds_bpermute_b32 v72, v255, v66
	ds_bpermute_b32 v73, v255, v67
	ds_bpermute_b32 v74, v255, v68
	ds_bpermute_b32 v75, v255, v69
	s_waitcnt lgkmcnt(0)
	global_store_dwordx4 v[70:71], v[72:75], off offset:256
	s_mov_b64 s[0:1], 0x200000
	v_pk_mul_f32 v[64:65], v[64:65], v[148:149] op_sel_hi:[1,0]
	v_max_f32_e32 v62, 0, v62
	v_mul_f32_e32 v68, v58, v58
	v_max_f32_e32 v58, 0, v63
	v_max_f32_e32 v59, 0, v59
	v_max_f32_e32 v60, 0, v60
	v_lshl_add_u64 v[66:67], v[150:151], 0, s[0:1]
	v_mul_f32_e32 v62, v62, v62
	v_mul_f32_e32 v58, v58, v58
	v_mul_f32_e32 v63, v59, v59
	v_max_f32_e32 v59, 0, v64
	v_mul_f32_e32 v64, v60, v60
	v_max_f32_e32 v60, 0, v65
	s_mov_b32 s0, 0x200000
	v_mul_f32_e32 v59, v59, v59
	v_max_f32_e32 v61, 0, v61
	v_mul_f32_e32 v60, v60, v60
	v_cvt_pk_bf16_f32 v58, v62, v58
	v_add_co_u32_e32 v62, vcc, s0, v150
	v_pk_mul_f32 v[52:53], v[52:53], v[148:149] op_sel_hi:[1,0]
	v_pk_mul_f32 v[50:51], v[50:51], v[148:149] op_sel_hi:[1,0]
	v_mul_f32_e32 v61, v61, v61
	v_cvt_pk_bf16_f32 v59, v59, v60
	v_cvt_pk_bf16_f32 v60, v68, v63
	v_addc_co_u32_e32 v63, vcc, 0, v151, vcc
	v_pk_mul_f32 v[56:57], v[56:57], v[148:149] op_sel_hi:[1,0]
	v_pk_mul_f32 v[54:55], v[54:55], v[148:149] op_sel_hi:[1,0]
	v_max_f32_e32 v50, 0, v50
	v_max_f32_e32 v51, 0, v51
	v_max_f32_e32 v52, 0, v52
	v_cvt_pk_bf16_f32 v61, v64, v61
	ds_bpermute_b32 v68, v255, v62
	ds_bpermute_b32 v69, v255, v63
	ds_bpermute_b32 v70, v255, v58
	ds_bpermute_b32 v71, v255, v59
	ds_bpermute_b32 v72, v255, v60
	ds_bpermute_b32 v73, v255, v61
	s_waitcnt lgkmcnt(0)
; __device__ __forceinline__ unsigned cvt_pk_bf16(float lo, float hi) { unsigned r; asm volatile("v_cvt_pk_bf16_f32 %0, %1, %2" : "=v"(r) : "v"(lo), "v"(hi)); return r; }
;     __device__ __forceinline__ void operator()(const f32x4 (&acc)[2][2][4][2], const Unit& u, int wr, int wc, int fr, int fq) const {
;     ...
;         for (int i = 0; i < 8; ++i) { const int ai = i >> 2, m = i & 3; bf16_t* rowp = O + (size_t)(row0 + ai * HALF + m * 16) * ldc + col0;
; #pragma unroll
;             for (int bj = 0; bj < 2; ++bj) { f32x4 v0 = acc[ai][bj][m][0] * rs[i], v1 = acc[ai][bj][m][1] * rs[i];
; #pragma unroll
;                 for (int e = 0; e < 4; ++e) { const float a = fmaxf(v0[e], 0.f), b = fmaxf(v1[e], 0.f); v0[e] = a * a; v1[e] = b * b; }
;                 u32x4 w; w.x = cvt_pk_bf16(v0[0], v0[1]); w.y = cvt_pk_bf16(v0[2], v0[3]); w.z = cvt_pk_bf16(v1[0], v1[1]); w.w = cvt_pk_bf16(v1[2], v1[3]);
;                 *(u32x4*)(rowp + bj * HALF) = w; } }
	global_store_dwordx4 v[68:69], v[70:73], off
	v_max_f32_e32 v54, 0, v54
	v_max_f32_e32 v53, 0, v53
	v_mul_f32_e32 v58, v50, v50
	v_max_f32_e32 v50, 0, v55
	v_mul_f32_e32 v55, v51, v51
	v_max_f32_e32 v51, 0, v56
	v_mul_f32_e32 v56, v52, v52
	v_max_f32_e32 v52, 0, v57
	v_mul_f32_e32 v50, v50, v50
	v_mul_f32_e32 v51, v51, v51
	v_mul_f32_e32 v52, v52, v52
	v_mul_f32_e32 v54, v54, v54
	v_mul_f32_e32 v53, v53, v53
	v_cvt_pk_bf16_f32 v50, v54, v50
	v_cvt_pk_bf16_f32 v51, v51, v52
	v_cvt_pk_bf16_f32 v52, v58, v55
	v_cvt_pk_bf16_f32 v53, v56, v53
	ds_bpermute_b32 v54, v255, v66
	ds_bpermute_b32 v55, v255, v67
	ds_bpermute_b32 v56, v255, v50
	ds_bpermute_b32 v57, v255, v51
	ds_bpermute_b32 v58, v255, v52
	ds_bpermute_b32 v59, v255, v53
	s_waitcnt lgkmcnt(0)
	global_store_dwordx4 v[54:55], v[56:59], off offset:256
	v_pk_mul_f32 v[26:27], v[26:27], v[144:145] op_sel_hi:[1,0]
	v_pk_mul_f32 v[30:31], v[30:31], v[144:145] op_sel_hi:[1,0]
	v_mov_b32_e32 v52, v149
	v_add_u32_e32 v50, 0x90, v142
	v_pk_mul_f32 v[42:43], v[42:43], v[52:53] op_sel_hi:[1,0]
	v_ashrrev_i32_e32 v51, 31, v50
	v_pk_mul_f32 v[46:47], v[46:47], v[52:53] op_sel_hi:[1,0]
	v_pk_mul_f32 v[44:45], v[44:45], v[52:53] op_sel_hi:[1,0]
	v_max_f32_e32 v42, 0, v42
	v_lshlrev_b64 v[50:51], 14, v[50:51]
	v_pk_mul_f32 v[48:49], v[48:49], v[52:53] op_sel_hi:[1,0]
	v_mul_f32_e32 v53, v42, v42
	v_max_f32_e32 v42, 0, v47
	v_max_f32_e32 v43, 0, v43
	v_max_f32_e32 v44, 0, v44
	v_lshl_add_u64 v[50:51], s[12:13], 0, v[50:51]
	v_max_f32_e32 v46, 0, v46
	v_mul_f32_e32 v42, v42, v42
	v_mul_f32_e32 v47, v43, v43
	v_max_f32_e32 v43, 0, v48
	v_mul_f32_e32 v48, v44, v44
	v_max_f32_e32 v44, 0, v49
	v_max_f32_e32 v45, 0, v45
	v_pk_mul_f32 v[34:35], v[34:35], v[52:53] op_sel_hi:[1,0]
	v_lshl_add_u64 v[50:51], v[50:51], 0, v[146:147]
	v_mul_f32_e32 v46, v46, v46
	v_mul_f32_e32 v43, v43, v43
	v_mul_f32_e32 v44, v44, v44
	v_mul_f32_e32 v45, v45, v45
	v_cvt_pk_bf16_f32 v42, v46, v42
	v_pk_mul_f32 v[38:39], v[38:39], v[52:53] op_sel_hi:[1,0]
	v_pk_mul_f32 v[36:37], v[36:37], v[52:53] op_sel_hi:[1,0]
	v_max_f32_e32 v34, 0, v34
	v_cvt_pk_bf16_f32 v43, v43, v44
	v_cvt_pk_bf16_f32 v44, v53, v47
	v_cvt_pk_bf16_f32 v45, v48, v45
	ds_bpermute_b32 v54, v255, v50
	ds_bpermute_b32 v55, v255, v51
	ds_bpermute_b32 v56, v255, v42
	ds_bpermute_b32 v57, v255, v43
	ds_bpermute_b32 v58, v255, v44
	ds_bpermute_b32 v59, v255, v45
	s_waitcnt lgkmcnt(0)
	global_store_dwordx4 v[54:55], v[56:59], off
	v_pk_mul_f32 v[40:41], v[40:41], v[52:53] op_sel_hi:[1,0]
	v_max_f32_e32 v35, 0, v35
	v_mul_f32_e32 v42, v34, v34
	v_max_f32_e32 v34, 0, v39
	v_max_f32_e32 v36, 0, v36
	v_max_f32_e32 v38, 0, v38
	v_mul_f32_e32 v34, v34, v34
	v_mul_f32_e32 v39, v35, v35
	v_max_f32_e32 v35, 0, v40
	v_mul_f32_e32 v40, v36, v36
	v_max_f32_e32 v36, 0, v41
	v_max_f32_e32 v37, 0, v37
	v_mul_f32_e32 v38, v38, v38
	v_mul_f32_e32 v35, v35, v35
	v_mul_f32_e32 v36, v36, v36
	v_mul_f32_e32 v37, v37, v37
	v_cvt_pk_bf16_f32 v34, v38, v34
	v_cvt_pk_bf16_f32 v35, v35, v36
	v_cvt_pk_bf16_f32 v36, v42, v39
	v_cvt_pk_bf16_f32 v37, v40, v37
	ds_bpermute_b32 v38, v255, v50
	ds_bpermute_b32 v39, v255, v51
	ds_bpermute_b32 v40, v255, v34
	ds_bpermute_b32 v41, v255, v35
	ds_bpermute_b32 v42, v255, v36
	ds_bpermute_b32 v43, v255, v37
	s_waitcnt lgkmcnt(0)
	global_store_dwordx4 v[38:39], v[40:43], off offset:256
	v_pk_mul_f32 v[28:29], v[28:29], v[144:145] op_sel_hi:[1,0]
	v_max_f32_e32 v26, 0, v26
	v_add_u32_e32 v34, 0xa0, v142
	v_ashrrev_i32_e32 v35, 31, v34
	v_lshlrev_b64 v[34:35], 14, v[34:35]
	v_pk_mul_f32 v[32:33], v[32:33], v[144:145] op_sel_hi:[1,0]
	v_mul_f32_e32 v36, v26, v26
	v_max_f32_e32 v26, 0, v31
	v_max_f32_e32 v27, 0, v27
	v_max_f32_e32 v28, 0, v28
	v_lshl_add_u64 v[34:35], s[12:13], 0, v[34:35]
	v_max_f32_e32 v30, 0, v30
	v_mul_f32_e32 v26, v26, v26
	v_mul_f32_e32 v31, v27, v27
	v_max_f32_e32 v27, 0, v32
	v_mul_f32_e32 v32, v28, v28
	v_max_f32_e32 v28, 0, v33
	v_max_f32_e32 v29, 0, v29
	v_pk_mul_f32 v[20:21], v[20:21], v[144:145] op_sel_hi:[1,0]
	v_pk_mul_f32 v[18:19], v[18:19], v[144:145] op_sel_hi:[1,0]
	v_lshl_add_u64 v[34:35], v[34:35], 0, v[146:147]
	v_mul_f32_e32 v30, v30, v30
	v_mul_f32_e32 v27, v27, v27
	v_mul_f32_e32 v28, v28, v28
	v_mul_f32_e32 v29, v29, v29
	v_cvt_pk_bf16_f32 v26, v30, v26
	v_pk_mul_f32 v[24:25], v[24:25], v[144:145] op_sel_hi:[1,0]
	v_pk_mul_f32 v[22:23], v[22:23], v[144:145] op_sel_hi:[1,0]
	v_max_f32_e32 v18, 0, v18
	v_max_f32_e32 v19, 0, v19
	v_max_f32_e32 v20, 0, v20
	v_cvt_pk_bf16_f32 v27, v27, v28
	v_cvt_pk_bf16_f32 v28, v36, v31
	v_cvt_pk_bf16_f32 v29, v32, v29
	ds_bpermute_b32 v36, v255, v34
	ds_bpermute_b32 v37, v255, v35
	ds_bpermute_b32 v38, v255, v26
	ds_bpermute_b32 v39, v255, v27
	ds_bpermute_b32 v40, v255, v28
	ds_bpermute_b32 v41, v255, v29
	s_waitcnt lgkmcnt(0)
; __device__ __forceinline__ unsigned cvt_pk_bf16(float lo, float hi) { unsigned r; asm volatile("v_cvt_pk_bf16_f32 %0, %1, %2" : "=v"(r) : "v"(lo), "v"(hi)); return r; }
; #define PG8_BAR __builtin_amdgcn_s_barrier()
;     __device__ __forceinline__ void operator()(const f32x4 (&acc)[2][2][4][2], const Unit& u, int wr, int wc, int fr, int fq) const {
;     ...
;         for (int i = 0; i < 8; ++i) { const int ai = i >> 2, m = i & 3; bf16_t* rowp = O + (size_t)(row0 + ai * HALF + m * 16) * ldc + col0;
; #pragma unroll
;             for (int bj = 0; bj < 2; ++bj) { f32x4 v0 = acc[ai][bj][m][0] * rs[i], v1 = acc[ai][bj][m][1] * rs[i];
; #pragma unroll
;                 for (int e = 0; e < 4; ++e) { const float a = fmaxf(v0[e], 0.f), b = fmaxf(v1[e], 0.f); v0[e] = a * a; v1[e] = b * b; }
;                 u32x4 w; w.x = cvt_pk_bf16(v0[0], v0[1]); w.y = cvt_pk_bf16(v0[2], v0[3]); w.z = cvt_pk_bf16(v1[0], v1[1]); w.w = cvt_pk_bf16(v1[2], v1[3]);
;                 *(u32x4*)(rowp + bj * HALF) = w; } }
; template <class Epi, class Sched, bool ALIGN_EPI = false, bool SP2 = false>
; __device__ __forceinline__ void gemm_phase(PG8_LAS unsigned char* lds, const Gemm g, const Sched& S, const Epi& E, const int wid_in) {
;     ...
;         if (!has_next) break;
;         E.init(acc, nxt, wr, wc, fr, fq);
;         cur = nxt; cA = nA; cB = nB; ++ui;
;         if constexpr (ALIGN_EPI) { if (wr == 1) PG8_BAR; }
	global_store_dwordx4 v[36:37], v[38:41], off
	v_max_f32_e32 v22, 0, v22
	v_max_f32_e32 v21, 0, v21
	v_mul_f32_e32 v26, v18, v18
	v_max_f32_e32 v18, 0, v23
	v_mul_f32_e32 v23, v19, v19
	v_max_f32_e32 v19, 0, v24
	v_mul_f32_e32 v24, v20, v20
	v_max_f32_e32 v20, 0, v25
	v_mul_f32_e32 v18, v18, v18
	v_mul_f32_e32 v19, v19, v19
	v_mul_f32_e32 v20, v20, v20
	v_mul_f32_e32 v22, v22, v22
	v_mul_f32_e32 v21, v21, v21
	v_cvt_pk_bf16_f32 v18, v22, v18
	v_cvt_pk_bf16_f32 v19, v19, v20
	v_cvt_pk_bf16_f32 v20, v26, v23
	v_cvt_pk_bf16_f32 v21, v24, v21
	ds_bpermute_b32 v22, v255, v34
	ds_bpermute_b32 v23, v255, v35
	ds_bpermute_b32 v24, v255, v18
	ds_bpermute_b32 v25, v255, v19
	ds_bpermute_b32 v26, v255, v20
	ds_bpermute_b32 v27, v255, v21
	s_waitcnt lgkmcnt(0)
	global_store_dwordx4 v[22:23], v[24:27], off offset:256
	s_andn2_b64 vcc, exec, s[6:7]
	s_mov_b64 s[0:1], -1
	v_mov_b32_e32 v20, v145
	v_add_u32_e32 v18, 0xb0, v142
	v_pk_mul_f32 v[10:11], v[10:11], v[20:21] op_sel_hi:[1,0]
	v_ashrrev_i32_e32 v19, 31, v18
	v_pk_mul_f32 v[14:15], v[14:15], v[20:21] op_sel_hi:[1,0]
	v_pk_mul_f32 v[12:13], v[12:13], v[20:21] op_sel_hi:[1,0]
	v_max_f32_e32 v10, 0, v10
	v_lshlrev_b64 v[18:19], 14, v[18:19]
	v_pk_mul_f32 v[16:17], v[16:17], v[20:21] op_sel_hi:[1,0]
	v_mul_f32_e32 v21, v10, v10
	v_max_f32_e32 v10, 0, v15
	v_max_f32_e32 v11, 0, v11
	v_max_f32_e32 v12, 0, v12
	v_lshl_add_u64 v[18:19], s[12:13], 0, v[18:19]
	v_max_f32_e32 v14, 0, v14
	v_mul_f32_e32 v10, v10, v10
	v_mul_f32_e32 v15, v11, v11
	v_max_f32_e32 v11, 0, v16
	v_mul_f32_e32 v16, v12, v12
	v_max_f32_e32 v12, 0, v17
	v_max_f32_e32 v13, 0, v13
	v_pk_mul_f32 v[4:5], v[4:5], v[20:21] op_sel_hi:[1,0]
	v_pk_mul_f32 v[2:3], v[2:3], v[20:21] op_sel_hi:[1,0]
	v_lshl_add_u64 v[18:19], v[18:19], 0, v[146:147]
	v_mul_f32_e32 v14, v14, v14
	v_mul_f32_e32 v11, v11, v11
	v_mul_f32_e32 v12, v12, v12
	v_mul_f32_e32 v13, v13, v13
	v_cvt_pk_bf16_f32 v10, v14, v10
	v_pk_mul_f32 v[8:9], v[8:9], v[20:21] op_sel_hi:[1,0]
	v_pk_mul_f32 v[6:7], v[6:7], v[20:21] op_sel_hi:[1,0]
	v_max_f32_e32 v2, 0, v2
	v_max_f32_e32 v3, 0, v3
	v_max_f32_e32 v4, 0, v4
	v_cvt_pk_bf16_f32 v11, v11, v12
	v_cvt_pk_bf16_f32 v12, v21, v15
	v_cvt_pk_bf16_f32 v13, v16, v13
	ds_bpermute_b32 v20, v255, v18
	ds_bpermute_b32 v21, v255, v19
	ds_bpermute_b32 v22, v255, v10
	ds_bpermute_b32 v23, v255, v11
	ds_bpermute_b32 v24, v255, v12
	ds_bpermute_b32 v25, v255, v13
	s_waitcnt lgkmcnt(0)
	global_store_dwordx4 v[20:21], v[22:25], off
	v_max_f32_e32 v5, 0, v5
	v_max_f32_e32 v6, 0, v6
	v_mul_f32_e32 v10, v2, v2
	v_max_f32_e32 v2, 0, v7
	v_mul_f32_e32 v7, v3, v3
	v_max_f32_e32 v3, 0, v8
	v_mul_f32_e32 v8, v4, v4
	v_max_f32_e32 v4, 0, v9
	v_mul_f32_e32 v2, v2, v2
	v_mul_f32_e32 v3, v3, v3
	v_mul_f32_e32 v4, v4, v4
	v_mul_f32_e32 v5, v5, v5
	v_readlane_b32 s50, v252, 33
	v_mul_f32_e32 v6, v6, v6
	v_cvt_pk_bf16_f32 v2, v6, v2
	v_cvt_pk_bf16_f32 v3, v3, v4
	v_cvt_pk_bf16_f32 v4, v10, v7
	v_cvt_pk_bf16_f32 v5, v8, v5
	ds_bpermute_b32 v10, v255, v18
	ds_bpermute_b32 v11, v255, v19
	ds_bpermute_b32 v12, v255, v2
	ds_bpermute_b32 v13, v255, v3
	ds_bpermute_b32 v14, v255, v4
	ds_bpermute_b32 v15, v255, v5
	s_waitcnt lgkmcnt(0)
	global_store_dwordx4 v[10:11], v[12:15], off offset:256
	v_readlane_b32 s51, v252, 34
	s_cbranch_vccnz .LBB0_476
	s_andn2_b64 vcc, exec, s[10:11]
	s_cbranch_vccnz .LBB0_475
	s_barrier
	s_branch .LBB0_475

; __global__ void __launch_bounds__(NWAVES * 64, 2) hybrid_fwd(Args a) {
	.amdhsa_kernel _Z10hybrid_fwd4Args
		.amdhsa_group_segment_fixed_size 0
		.amdhsa_private_segment_fixed_size 0
		.amdhsa_kernarg_size 368
		.amdhsa_user_sgpr_count 2
		.amdhsa_user_sgpr_dispatch_ptr 0
		.amdhsa_user_sgpr_queue_ptr 0
		.amdhsa_user_sgpr_kernarg_segment_ptr 1
		.amdhsa_user_sgpr_dispatch_id 0
		.amdhsa_user_sgpr_kernarg_preload_length 0
		.amdhsa_user_sgpr_kernarg_preload_offset 0
		.amdhsa_user_sgpr_private_segment_size 0
		.amdhsa_uses_dynamic_stack 0
		.amdhsa_enable_private_segment 0
		.amdhsa_system_sgpr_workgroup_id_x 1
		.amdhsa_system_sgpr_workgroup_id_y 0
		.amdhsa_system_sgpr_workgroup_id_z 0
		.amdhsa_system_sgpr_workgroup_info 0
		.amdhsa_system_vgpr_workitem_id 2
		.amdhsa_next_free_vgpr 256
		.amdhsa_next_free_sgpr 102
		.amdhsa_accum_offset 256
		.amdhsa_reserve_vcc 1
		.amdhsa_float_round_mode_32 0
		.amdhsa_float_round_mode_16_64 0
		.amdhsa_float_denorm_mode_32 3
		.amdhsa_float_denorm_mode_16_64 3
		.amdhsa_dx10_clamp 1
		.amdhsa_ieee_mode 1
		.amdhsa_fp16_overflow 0
		.amdhsa_tg_split 0
		.amdhsa_exception_fp_ieee_invalid_op 0
		.amdhsa_exception_fp_denorm_src 0
		.amdhsa_exception_fp_ieee_div_zero 0
		.amdhsa_exception_fp_ieee_overflow 0
		.amdhsa_exception_fp_ieee_underflow 0
		.amdhsa_exception_fp_ieee_inexact 0
		.amdhsa_exception_int_div_zero 0
	.end_amdhsa_kernel

; __global__ void __launch_bounds__(NWAVES * 64, 2) hybrid_fwd(Args a) {
amdhsa.kernels:
  - .agpr_count:     0
    .args:
      - .offset:         0
        .size:           112
        .value_kind:     by_value
      - .offset:         112
        .size:           4
        .value_kind:     hidden_block_count_x
      - .offset:         116
        .size:           4
        .value_kind:     hidden_block_count_y
      - .offset:         120
        .size:           4
        .value_kind:     hidden_block_count_z
      - .offset:         124
        .size:           2
        .value_kind:     hidden_group_size_x
      - .offset:         126
        .size:           2
        .value_kind:     hidden_group_size_y
      - .offset:         128
        .size:           2
        .value_kind:     hidden_group_size_z
      - .offset:         130
        .size:           2
        .value_kind:     hidden_remainder_x
      - .offset:         132
        .size:           2
        .value_kind:     hidden_remainder_y
      - .offset:         134
        .size:           2
        .value_kind:     hidden_remainder_z
      - .offset:         152
        .size:           8
        .value_kind:     hidden_global_offset_x
      - .offset:         160
        .size:           8
        .value_kind:     hidden_global_offset_y
      - .offset:         168
        .size:           8
        .value_kind:     hidden_global_offset_z
      - .offset:         176
        .size:           2
        .value_kind:     hidden_grid_dims
      - .offset:         200
        .size:           8
        .value_kind:     hidden_multigrid_sync_arg
      - .offset:         232
        .size:           4
        .value_kind:     hidden_dynamic_lds_size
    .group_segment_fixed_size: 0
    .kernarg_segment_align: 8
    .kernarg_segment_size: 368
    .language:       OpenCL C
    .language_version:
      - 2
      - 0
    .max_flat_workgroup_size: 512
    .name:           _Z10hybrid_fwd4Args
    .private_segment_fixed_size: 0
    .sgpr_count:     108
    .sgpr_spill_count: 164
    .symbol:         _Z10hybrid_fwd4Args.kd
    .uniform_work_group_size: 1
    .uses_dynamic_stack: false
    .vgpr_count:     256
    .vgpr_spill_count: 0
    .wavefront_size: 64
